# PEER coefficient stage: reduce-scatter of the 16 dots over the 8 sub lanes, 2 gelu per lane instead of 16 on one lane
# speedup vs baseline: 1.0063x; 1.0063x over previous
; __device__ __forceinline__ float xor1(float v) { return dppf<0xB1>(v); }
; __device__ __forceinline__ float xor2(float v) { return dppf<0x4E>(v); }
; __device__ __forceinline__ float xor4s(float v) { return dppf<0x141>(v); }
; __device__ __forceinline__ float gelu_erf(float x) { return 0.5f * x * (1.f + erff(x * 0.70710678118654752f)); }
; __device__ __forceinline__ void p8_peer_gather(Frame& F) {
;     ...
;     for (int q = 0; q < 9; ++q) { const int j = q < 8 ? wave + 8 * q : 64;
; #pragma unroll
;         for (int i = 0; i < 16; ++i) { float v = (float)acc[q][i]; v += xor1(v); v += xor2(v); v += xor4s(v);
;             if (sub == 0) { if (q < 8) { const int pos = j * 128 + pg * 16 + i; cf_s[pos] = cf_pack(cf_s[pos] * gelu_erf(v * (1.f / 73728.f)) * 0.125f); } else part_s[wave * 128 + pg * 16 + i] = v; } } }
.LBB0_1775:
	s_waitcnt vmcnt(0)
	s_mov_b32 s42, 0xaaaaaaaa
	s_mov_b32 s43, 0xaaaaaaaa
	s_mov_b32 s44, 0xcccccccc
	s_mov_b32 s45, 0xcccccccc
	s_mov_b32 s46, 0xf0f0f0f0
	s_mov_b32 s47, 0xf0f0f0f0
	s_mov_b32 s48, 0x378e98ab
	s_mov_b32 s49, 0x3b7cd369
	s_mov_b32 s50, 0xbcc618b2
	s_mov_b32 s51, 0x3dda74e4
	s_mov_b32 s52, 0x3f228afd
	s_mov_b32 s53, 0x3e03c728
	s_mov_b32 s54, 0xbfb8aa3b
	s_mov_b32 s55, 0x42ce8ed0
	s_mov_b32 s56, 0xc2b17218
	s_mov_b32 s57, 0x7fffffff
	v_or_b32_e32 v0, s35, v235
	v_add_u32_e32 v0, v0, v234
	v_lshlrev_b32_e32 v0, 2, v0
	v_add_u32_e32 v1, 0x10400, v0
	v_cvt_f32_i32_e32 v240, v240
	v_cvt_f32_i32_e32 v239, v239
	v_cvt_f32_i32_e32 v236, v236
	v_cvt_f32_i32_e32 v233, v233
	v_cvt_f32_i32_e32 v232, v232
	v_cvt_f32_i32_e32 v231, v231
	v_cvt_f32_i32_e32 v230, v230
	v_cvt_f32_i32_e32 v229, v229
	v_cvt_f32_i32_e32 v228, v228
	v_cvt_f32_i32_e32 v227, v227
	v_cvt_f32_i32_e32 v226, v226
	v_cvt_f32_i32_e32 v225, v225
	v_cvt_f32_i32_e32 v224, v224
	v_cvt_f32_i32_e32 v223, v223
	v_cvt_f32_i32_e32 v222, v222
	v_cvt_f32_i32_e32 v221, v221
	v_cndmask_b32_e64 v3, v239, v240, s[42:43]
	v_cndmask_b32_e64 v5, v233, v236, s[42:43]
	v_cndmask_b32_e64 v2, v240, v239, s[42:43]
	v_cndmask_b32_e64 v4, v236, v233, s[42:43]
	v_add_f32_dpp v240, v3, v2 quad_perm:[1,0,3,2] row_mask:0xf bank_mask:0xf bound_ctrl:1
	v_add_f32_dpp v236, v5, v4 quad_perm:[1,0,3,2] row_mask:0xf bank_mask:0xf bound_ctrl:1
	v_cndmask_b32_e64 v3, v231, v232, s[42:43]
	v_cndmask_b32_e64 v5, v229, v230, s[42:43]
	v_cndmask_b32_e64 v2, v232, v231, s[42:43]
	v_cndmask_b32_e64 v4, v230, v229, s[42:43]
	v_add_f32_dpp v232, v3, v2 quad_perm:[1,0,3,2] row_mask:0xf bank_mask:0xf bound_ctrl:1
	v_add_f32_dpp v230, v5, v4 quad_perm:[1,0,3,2] row_mask:0xf bank_mask:0xf bound_ctrl:1
	v_cndmask_b32_e64 v3, v227, v228, s[42:43]
	v_cndmask_b32_e64 v5, v225, v226, s[42:43]
	v_cndmask_b32_e64 v2, v228, v227, s[42:43]
	v_cndmask_b32_e64 v4, v226, v225, s[42:43]
	v_add_f32_dpp v228, v3, v2 quad_perm:[1,0,3,2] row_mask:0xf bank_mask:0xf bound_ctrl:1
	v_add_f32_dpp v226, v5, v4 quad_perm:[1,0,3,2] row_mask:0xf bank_mask:0xf bound_ctrl:1
	v_cndmask_b32_e64 v3, v223, v224, s[42:43]
	v_cndmask_b32_e64 v5, v221, v222, s[42:43]
	v_cndmask_b32_e64 v2, v224, v223, s[42:43]
	v_cndmask_b32_e64 v4, v222, v221, s[42:43]
	v_add_f32_dpp v224, v3, v2 quad_perm:[1,0,3,2] row_mask:0xf bank_mask:0xf bound_ctrl:1
	v_add_f32_dpp v222, v5, v4 quad_perm:[1,0,3,2] row_mask:0xf bank_mask:0xf bound_ctrl:1
	v_cndmask_b32_e64 v3, v236, v240, s[44:45]
	v_cndmask_b32_e64 v5, v230, v232, s[44:45]
	v_cndmask_b32_e64 v2, v240, v236, s[44:45]
	v_cndmask_b32_e64 v4, v232, v230, s[44:45]
	v_add_f32_dpp v240, v3, v2 quad_perm:[2,3,0,1] row_mask:0xf bank_mask:0xf bound_ctrl:1
	v_add_f32_dpp v232, v5, v4 quad_perm:[2,3,0,1] row_mask:0xf bank_mask:0xf bound_ctrl:1
	v_cndmask_b32_e64 v3, v226, v228, s[44:45]
	v_cndmask_b32_e64 v5, v222, v224, s[44:45]
	v_cndmask_b32_e64 v2, v228, v226, s[44:45]
	v_cndmask_b32_e64 v4, v224, v222, s[44:45]
	v_add_f32_dpp v228, v3, v2 quad_perm:[2,3,0,1] row_mask:0xf bank_mask:0xf bound_ctrl:1
	v_add_f32_dpp v224, v5, v4 quad_perm:[2,3,0,1] row_mask:0xf bank_mask:0xf bound_ctrl:1
	v_cndmask_b32_e64 v3, v232, v240, s[46:47]
	v_cndmask_b32_e64 v5, v224, v228, s[46:47]
	v_cndmask_b32_e64 v2, v240, v232, s[46:47]
	v_cndmask_b32_e64 v4, v228, v224, s[46:47]
	v_mov_b32_dpp v6, v3 row_half_mirror row_mask:0xf bank_mask:0xf bound_ctrl:1
	v_mov_b32_dpp v7, v5 row_half_mirror row_mask:0xf bank_mask:0xf bound_ctrl:1
	s_nop 1
	v_add_f32_dpp v240, v6, v2 quad_perm:[3,2,1,0] row_mask:0xf bank_mask:0xf bound_ctrl:1
	v_add_f32_dpp v228, v7, v4 quad_perm:[3,2,1,0] row_mask:0xf bank_mask:0xf bound_ctrl:1
	ds_read_b32 v8, v0 offset:33280
	v_mul_f32_e32 v2, 0x37638e39, v240
	v_mul_f32_e32 v3, 0x3f3504f3, v2
	v_mov_b32_e32 v4, 0xb9c68948
	v_fma_f32 v4, |v3|, s48, v4
	v_fma_f32 v4, |v3|, v4, s49
	v_fma_f32 v4, |v3|, v4, s50
	v_fma_f32 v4, |v3|, v4, s51
	v_fma_f32 v4, |v3|, v4, s52
	v_fma_f32 v4, |v3|, v4, s53
	v_fma_f32 v4, |v3|, v4, |v3|
	v_mul_f32_e32 v5, 0xbfb8aa3b, v4
	v_fma_f32 v6, v4, s54, -v5
	v_rndne_f32_e32 v7, v5
	v_fmamk_f32 v6, v4, 0xb2a5705f, v6
	v_sub_f32_e32 v5, v5, v7
	v_add_f32_e32 v5, v5, v6
	v_exp_f32_e32 v5, v5
	v_cvt_i32_f32_e32 v6, v7
	v_cmp_nlt_f32_e64 s[4:5], s55, v4
	v_ldexp_f32 v5, v5, v6
	v_mov_b32_e32 v6, 0x7f800000
	v_cndmask_b32_e64 v5, 0, v5, s[4:5]
	v_cmp_ngt_f32_e64 s[4:5], s56, v4
	v_mul_f32_e32 v7, v3, v3
	s_nop 1
	v_cndmask_b32_e64 v4, v6, v5, s[4:5]
	v_sub_f32_e32 v4, 1.0, v4
	v_mov_b32_e32 v6, 0x3ba10414
	v_fmac_f32_e32 v6, 0xba1345e1, v7
	v_fmaak_f32 v6, v7, v6, 0xbcdac9b8
	v_fmaak_f32 v6, v7, v6, 0x3de703be
	v_fmaak_f32 v6, v7, v6, 0xbec09330
	v_fmaak_f32 v7, v7, v6, 0x3e0375d0
	v_cmp_lt_f32_e64 s[4:5], |v3|, 1.0
	v_fma_f32 v7, |v3|, v7, |v3|
	v_mul_f32_e32 v2, 0.5, v2
	v_cndmask_b32_e64 v4, v4, v7, s[4:5]
	v_bfi_b32 v3, s57, v4, v3
	v_add_f32_e32 v3, 1.0, v3
	v_mul_f32_e32 v3, v2, v3
	s_waitcnt lgkmcnt(0)
; __device__ __forceinline__ float xor1(float v) { return dppf<0xB1>(v); }
; __device__ __forceinline__ float xor2(float v) { return dppf<0x4E>(v); }
; __device__ __forceinline__ float xor4s(float v) { return dppf<0x141>(v); }
; __device__ __forceinline__ float gelu_erf(float x) { return 0.5f * x * (1.f + erff(x * 0.70710678118654752f)); }
; __device__ __forceinline__ void p8_peer_gather(Frame& F) {
;     ...
;     for (int q = 0; q < 9; ++q) { const int j = q < 8 ? wave + 8 * q : 64;
; #pragma unroll
;         for (int i = 0; i < 16; ++i) { float v = (float)acc[q][i]; v += xor1(v); v += xor2(v); v += xor4s(v);
;             if (sub == 0) { if (q < 8) { const int pos = j * 128 + pg * 16 + i; cf_s[pos] = cf_pack(cf_s[pos] * gelu_erf(v * (1.f / 73728.f)) * 0.125f); } else part_s[wave * 128 + pg * 16 + i] = v; } } }
	v_mul_f32_e32 v8, v8, v3
	v_mul_f32_e32 v8, 0x3e000000, v8
	v_cvt_pk_f16_f32 v8, v8, v8
	ds_write_b32 v0, v8 offset:33280
	ds_read_b32 v8, v0 offset:33312
	v_mul_f32_e32 v2, 0x37638e39, v228
	v_mul_f32_e32 v3, 0x3f3504f3, v2
	v_mov_b32_e32 v4, 0xb9c68948
	v_fma_f32 v4, |v3|, s48, v4
	v_fma_f32 v4, |v3|, v4, s49
	v_fma_f32 v4, |v3|, v4, s50
	v_fma_f32 v4, |v3|, v4, s51
	v_fma_f32 v4, |v3|, v4, s52
	v_fma_f32 v4, |v3|, v4, s53
	v_fma_f32 v4, |v3|, v4, |v3|
	v_mul_f32_e32 v5, 0xbfb8aa3b, v4
	v_fma_f32 v6, v4, s54, -v5
	v_rndne_f32_e32 v7, v5
	v_fmamk_f32 v6, v4, 0xb2a5705f, v6
	v_sub_f32_e32 v5, v5, v7
	v_add_f32_e32 v5, v5, v6
	v_exp_f32_e32 v5, v5
	v_cvt_i32_f32_e32 v6, v7
	v_cmp_nlt_f32_e64 s[4:5], s55, v4
	v_ldexp_f32 v5, v5, v6
	v_mov_b32_e32 v6, 0x7f800000
	v_cndmask_b32_e64 v5, 0, v5, s[4:5]
	v_cmp_ngt_f32_e64 s[4:5], s56, v4
	v_mul_f32_e32 v7, v3, v3
	s_nop 1
	v_cndmask_b32_e64 v4, v6, v5, s[4:5]
	v_sub_f32_e32 v4, 1.0, v4
	v_mov_b32_e32 v6, 0x3ba10414
	v_fmac_f32_e32 v6, 0xba1345e1, v7
	v_fmaak_f32 v6, v7, v6, 0xbcdac9b8
	v_fmaak_f32 v6, v7, v6, 0x3de703be
	v_fmaak_f32 v6, v7, v6, 0xbec09330
	v_fmaak_f32 v7, v7, v6, 0x3e0375d0
	v_cmp_lt_f32_e64 s[4:5], |v3|, 1.0
	v_fma_f32 v7, |v3|, v7, |v3|
	v_mul_f32_e32 v2, 0.5, v2
	v_cndmask_b32_e64 v4, v4, v7, s[4:5]
	v_bfi_b32 v3, s57, v4, v3
	v_add_f32_e32 v3, 1.0, v3
	v_mul_f32_e32 v3, v2, v3
	s_waitcnt lgkmcnt(0)
	v_mul_f32_e32 v8, v8, v3
	v_mul_f32_e32 v8, 0x3e000000, v8
	v_cvt_pk_f16_f32 v8, v8, v8
	ds_write_b32 v0, v8 offset:33312
	v_cvt_f32_i32_e32 v220, v220
	v_cvt_f32_i32_e32 v219, v219
	v_cvt_f32_i32_e32 v218, v218
	v_cvt_f32_i32_e32 v217, v217
	v_cvt_f32_i32_e32 v216, v216
	v_cvt_f32_i32_e32 v215, v215
	v_cvt_f32_i32_e32 v214, v214
	v_cvt_f32_i32_e32 v213, v213
	v_cvt_f32_i32_e32 v212, v212
	v_cvt_f32_i32_e32 v211, v211
	v_cvt_f32_i32_e32 v210, v210
	v_cvt_f32_i32_e32 v209, v209
	v_cvt_f32_i32_e32 v208, v208
	v_cvt_f32_i32_e32 v207, v207
	v_cvt_f32_i32_e32 v206, v206
	v_cvt_f32_i32_e32 v205, v205
	v_cndmask_b32_e64 v3, v219, v220, s[42:43]
	v_cndmask_b32_e64 v5, v217, v218, s[42:43]
	v_cndmask_b32_e64 v2, v220, v219, s[42:43]
	v_cndmask_b32_e64 v4, v218, v217, s[42:43]
	v_add_f32_dpp v220, v3, v2 quad_perm:[1,0,3,2] row_mask:0xf bank_mask:0xf bound_ctrl:1
	v_add_f32_dpp v218, v5, v4 quad_perm:[1,0,3,2] row_mask:0xf bank_mask:0xf bound_ctrl:1
	v_cndmask_b32_e64 v3, v215, v216, s[42:43]
	v_cndmask_b32_e64 v5, v213, v214, s[42:43]
	v_cndmask_b32_e64 v2, v216, v215, s[42:43]
	v_cndmask_b32_e64 v4, v214, v213, s[42:43]
	v_add_f32_dpp v216, v3, v2 quad_perm:[1,0,3,2] row_mask:0xf bank_mask:0xf bound_ctrl:1
	v_add_f32_dpp v214, v5, v4 quad_perm:[1,0,3,2] row_mask:0xf bank_mask:0xf bound_ctrl:1
	v_cndmask_b32_e64 v3, v211, v212, s[42:43]
	v_cndmask_b32_e64 v5, v209, v210, s[42:43]
	v_cndmask_b32_e64 v2, v212, v211, s[42:43]
	v_cndmask_b32_e64 v4, v210, v209, s[42:43]
	v_add_f32_dpp v212, v3, v2 quad_perm:[1,0,3,2] row_mask:0xf bank_mask:0xf bound_ctrl:1
	v_add_f32_dpp v210, v5, v4 quad_perm:[1,0,3,2] row_mask:0xf bank_mask:0xf bound_ctrl:1
	v_cndmask_b32_e64 v3, v207, v208, s[42:43]
	v_cndmask_b32_e64 v5, v205, v206, s[42:43]
	v_cndmask_b32_e64 v2, v208, v207, s[42:43]
	v_cndmask_b32_e64 v4, v206, v205, s[42:43]
	v_add_f32_dpp v208, v3, v2 quad_perm:[1,0,3,2] row_mask:0xf bank_mask:0xf bound_ctrl:1
	v_add_f32_dpp v206, v5, v4 quad_perm:[1,0,3,2] row_mask:0xf bank_mask:0xf bound_ctrl:1
	v_cndmask_b32_e64 v3, v218, v220, s[44:45]
	v_cndmask_b32_e64 v5, v214, v216, s[44:45]
	v_cndmask_b32_e64 v2, v220, v218, s[44:45]
	v_cndmask_b32_e64 v4, v216, v214, s[44:45]
	v_add_f32_dpp v220, v3, v2 quad_perm:[2,3,0,1] row_mask:0xf bank_mask:0xf bound_ctrl:1
	v_add_f32_dpp v216, v5, v4 quad_perm:[2,3,0,1] row_mask:0xf bank_mask:0xf bound_ctrl:1
	v_cndmask_b32_e64 v3, v210, v212, s[44:45]
	v_cndmask_b32_e64 v5, v206, v208, s[44:45]
	v_cndmask_b32_e64 v2, v212, v210, s[44:45]
	v_cndmask_b32_e64 v4, v208, v206, s[44:45]
	v_add_f32_dpp v212, v3, v2 quad_perm:[2,3,0,1] row_mask:0xf bank_mask:0xf bound_ctrl:1
	v_add_f32_dpp v208, v5, v4 quad_perm:[2,3,0,1] row_mask:0xf bank_mask:0xf bound_ctrl:1
	v_cndmask_b32_e64 v3, v216, v220, s[46:47]
	v_cndmask_b32_e64 v5, v208, v212, s[46:47]
	v_cndmask_b32_e64 v2, v220, v216, s[46:47]
	v_cndmask_b32_e64 v4, v212, v208, s[46:47]
	v_mov_b32_dpp v6, v3 row_half_mirror row_mask:0xf bank_mask:0xf bound_ctrl:1
	v_mov_b32_dpp v7, v5 row_half_mirror row_mask:0xf bank_mask:0xf bound_ctrl:1
	s_nop 1
	v_add_f32_dpp v220, v6, v2 quad_perm:[3,2,1,0] row_mask:0xf bank_mask:0xf bound_ctrl:1
	v_add_f32_dpp v212, v7, v4 quad_perm:[3,2,1,0] row_mask:0xf bank_mask:0xf bound_ctrl:1
	ds_read_b32 v8, v0 offset:37376
	v_mul_f32_e32 v2, 0x37638e39, v220
	v_mul_f32_e32 v3, 0x3f3504f3, v2
	v_mov_b32_e32 v4, 0xb9c68948
	v_fma_f32 v4, |v3|, s48, v4
	v_fma_f32 v4, |v3|, v4, s49
	v_fma_f32 v4, |v3|, v4, s50
	v_fma_f32 v4, |v3|, v4, s51
	v_fma_f32 v4, |v3|, v4, s52
	v_fma_f32 v4, |v3|, v4, s53
	v_fma_f32 v4, |v3|, v4, |v3|
	v_mul_f32_e32 v5, 0xbfb8aa3b, v4
	v_fma_f32 v6, v4, s54, -v5
	v_rndne_f32_e32 v7, v5
	v_fmamk_f32 v6, v4, 0xb2a5705f, v6
	v_sub_f32_e32 v5, v5, v7
	v_add_f32_e32 v5, v5, v6
	v_exp_f32_e32 v5, v5
	v_cvt_i32_f32_e32 v6, v7
	v_cmp_nlt_f32_e64 s[4:5], s55, v4
	v_ldexp_f32 v5, v5, v6
	v_mov_b32_e32 v6, 0x7f800000
	v_cndmask_b32_e64 v5, 0, v5, s[4:5]
	v_cmp_ngt_f32_e64 s[4:5], s56, v4
	v_mul_f32_e32 v7, v3, v3
	s_nop 1
	v_cndmask_b32_e64 v4, v6, v5, s[4:5]
	v_sub_f32_e32 v4, 1.0, v4
	v_mov_b32_e32 v6, 0x3ba10414
	v_fmac_f32_e32 v6, 0xba1345e1, v7
	v_fmaak_f32 v6, v7, v6, 0xbcdac9b8
	v_fmaak_f32 v6, v7, v6, 0x3de703be
	v_fmaak_f32 v6, v7, v6, 0xbec09330
	v_fmaak_f32 v7, v7, v6, 0x3e0375d0
	v_cmp_lt_f32_e64 s[4:5], |v3|, 1.0
	v_fma_f32 v7, |v3|, v7, |v3|
	v_mul_f32_e32 v2, 0.5, v2
	v_cndmask_b32_e64 v4, v4, v7, s[4:5]
	v_bfi_b32 v3, s57, v4, v3
	v_add_f32_e32 v3, 1.0, v3
	v_mul_f32_e32 v3, v2, v3
	s_waitcnt lgkmcnt(0)
; __device__ __forceinline__ float xor1(float v) { return dppf<0xB1>(v); }
; __device__ __forceinline__ float xor2(float v) { return dppf<0x4E>(v); }
; __device__ __forceinline__ float xor4s(float v) { return dppf<0x141>(v); }
; __device__ __forceinline__ float gelu_erf(float x) { return 0.5f * x * (1.f + erff(x * 0.70710678118654752f)); }
; __device__ __forceinline__ void p8_peer_gather(Frame& F) {
;     ...
;     for (int q = 0; q < 9; ++q) { const int j = q < 8 ? wave + 8 * q : 64;
; #pragma unroll
;         for (int i = 0; i < 16; ++i) { float v = (float)acc[q][i]; v += xor1(v); v += xor2(v); v += xor4s(v);
;             if (sub == 0) { if (q < 8) { const int pos = j * 128 + pg * 16 + i; cf_s[pos] = cf_pack(cf_s[pos] * gelu_erf(v * (1.f / 73728.f)) * 0.125f); } else part_s[wave * 128 + pg * 16 + i] = v; } } }
	v_mul_f32_e32 v8, v8, v3
	v_mul_f32_e32 v8, 0x3e000000, v8
	v_cvt_pk_f16_f32 v8, v8, v8
	ds_write_b32 v0, v8 offset:37376
	ds_read_b32 v8, v0 offset:37408
	v_mul_f32_e32 v2, 0x37638e39, v212
	v_mul_f32_e32 v3, 0x3f3504f3, v2
	v_mov_b32_e32 v4, 0xb9c68948
	v_fma_f32 v4, |v3|, s48, v4
	v_fma_f32 v4, |v3|, v4, s49
	v_fma_f32 v4, |v3|, v4, s50
	v_fma_f32 v4, |v3|, v4, s51
	v_fma_f32 v4, |v3|, v4, s52
	v_fma_f32 v4, |v3|, v4, s53
	v_fma_f32 v4, |v3|, v4, |v3|
	v_mul_f32_e32 v5, 0xbfb8aa3b, v4
	v_fma_f32 v6, v4, s54, -v5
	v_rndne_f32_e32 v7, v5
	v_fmamk_f32 v6, v4, 0xb2a5705f, v6
	v_sub_f32_e32 v5, v5, v7
	v_add_f32_e32 v5, v5, v6
	v_exp_f32_e32 v5, v5
	v_cvt_i32_f32_e32 v6, v7
	v_cmp_nlt_f32_e64 s[4:5], s55, v4
	v_ldexp_f32 v5, v5, v6
	v_mov_b32_e32 v6, 0x7f800000
	v_cndmask_b32_e64 v5, 0, v5, s[4:5]
	v_cmp_ngt_f32_e64 s[4:5], s56, v4
	v_mul_f32_e32 v7, v3, v3
	s_nop 1
	v_cndmask_b32_e64 v4, v6, v5, s[4:5]
	v_sub_f32_e32 v4, 1.0, v4
	v_mov_b32_e32 v6, 0x3ba10414
	v_fmac_f32_e32 v6, 0xba1345e1, v7
	v_fmaak_f32 v6, v7, v6, 0xbcdac9b8
	v_fmaak_f32 v6, v7, v6, 0x3de703be
	v_fmaak_f32 v6, v7, v6, 0xbec09330
	v_fmaak_f32 v7, v7, v6, 0x3e0375d0
	v_cmp_lt_f32_e64 s[4:5], |v3|, 1.0
	v_fma_f32 v7, |v3|, v7, |v3|
	v_mul_f32_e32 v2, 0.5, v2
	v_cndmask_b32_e64 v4, v4, v7, s[4:5]
	v_bfi_b32 v3, s57, v4, v3
	v_add_f32_e32 v3, 1.0, v3
	v_mul_f32_e32 v3, v2, v3
	s_waitcnt lgkmcnt(0)
	v_mul_f32_e32 v8, v8, v3
	v_mul_f32_e32 v8, 0x3e000000, v8
	v_cvt_pk_f16_f32 v8, v8, v8
	ds_write_b32 v0, v8 offset:37408
	v_cvt_f32_i32_e32 v204, v204
	v_cvt_f32_i32_e32 v203, v203
	v_cvt_f32_i32_e32 v202, v202
	v_cvt_f32_i32_e32 v201, v201
	v_cvt_f32_i32_e32 v200, v200
	v_cvt_f32_i32_e32 v199, v199
	v_cvt_f32_i32_e32 v198, v198
	v_cvt_f32_i32_e32 v197, v197
	v_cvt_f32_i32_e32 v196, v196
	v_cvt_f32_i32_e32 v195, v195
	v_cvt_f32_i32_e32 v194, v194
	v_cvt_f32_i32_e32 v193, v193
	v_cvt_f32_i32_e32 v192, v192
	v_cvt_f32_i32_e32 v191, v191
	v_cvt_f32_i32_e32 v190, v190
	v_cvt_f32_i32_e32 v189, v189
	v_cndmask_b32_e64 v3, v203, v204, s[42:43]
	v_cndmask_b32_e64 v5, v201, v202, s[42:43]
	v_cndmask_b32_e64 v2, v204, v203, s[42:43]
	v_cndmask_b32_e64 v4, v202, v201, s[42:43]
	v_add_f32_dpp v204, v3, v2 quad_perm:[1,0,3,2] row_mask:0xf bank_mask:0xf bound_ctrl:1
	v_add_f32_dpp v202, v5, v4 quad_perm:[1,0,3,2] row_mask:0xf bank_mask:0xf bound_ctrl:1
	v_cndmask_b32_e64 v3, v199, v200, s[42:43]
	v_cndmask_b32_e64 v5, v197, v198, s[42:43]
	v_cndmask_b32_e64 v2, v200, v199, s[42:43]
	v_cndmask_b32_e64 v4, v198, v197, s[42:43]
	v_add_f32_dpp v200, v3, v2 quad_perm:[1,0,3,2] row_mask:0xf bank_mask:0xf bound_ctrl:1
	v_add_f32_dpp v198, v5, v4 quad_perm:[1,0,3,2] row_mask:0xf bank_mask:0xf bound_ctrl:1
	v_cndmask_b32_e64 v3, v195, v196, s[42:43]
	v_cndmask_b32_e64 v5, v193, v194, s[42:43]
	v_cndmask_b32_e64 v2, v196, v195, s[42:43]
	v_cndmask_b32_e64 v4, v194, v193, s[42:43]
	v_add_f32_dpp v196, v3, v2 quad_perm:[1,0,3,2] row_mask:0xf bank_mask:0xf bound_ctrl:1
	v_add_f32_dpp v194, v5, v4 quad_perm:[1,0,3,2] row_mask:0xf bank_mask:0xf bound_ctrl:1
	v_cndmask_b32_e64 v3, v191, v192, s[42:43]
	v_cndmask_b32_e64 v5, v189, v190, s[42:43]
	v_cndmask_b32_e64 v2, v192, v191, s[42:43]
	v_cndmask_b32_e64 v4, v190, v189, s[42:43]
	v_add_f32_dpp v192, v3, v2 quad_perm:[1,0,3,2] row_mask:0xf bank_mask:0xf bound_ctrl:1
	v_add_f32_dpp v190, v5, v4 quad_perm:[1,0,3,2] row_mask:0xf bank_mask:0xf bound_ctrl:1
	v_cndmask_b32_e64 v3, v202, v204, s[44:45]
	v_cndmask_b32_e64 v5, v198, v200, s[44:45]
	v_cndmask_b32_e64 v2, v204, v202, s[44:45]
	v_cndmask_b32_e64 v4, v200, v198, s[44:45]
	v_add_f32_dpp v204, v3, v2 quad_perm:[2,3,0,1] row_mask:0xf bank_mask:0xf bound_ctrl:1
	v_add_f32_dpp v200, v5, v4 quad_perm:[2,3,0,1] row_mask:0xf bank_mask:0xf bound_ctrl:1
	v_cndmask_b32_e64 v3, v194, v196, s[44:45]
	v_cndmask_b32_e64 v5, v190, v192, s[44:45]
	v_cndmask_b32_e64 v2, v196, v194, s[44:45]
	v_cndmask_b32_e64 v4, v192, v190, s[44:45]
	v_add_f32_dpp v196, v3, v2 quad_perm:[2,3,0,1] row_mask:0xf bank_mask:0xf bound_ctrl:1
	v_add_f32_dpp v192, v5, v4 quad_perm:[2,3,0,1] row_mask:0xf bank_mask:0xf bound_ctrl:1
	v_cndmask_b32_e64 v3, v200, v204, s[46:47]
	v_cndmask_b32_e64 v5, v192, v196, s[46:47]
	v_cndmask_b32_e64 v2, v204, v200, s[46:47]
	v_cndmask_b32_e64 v4, v196, v192, s[46:47]
	v_mov_b32_dpp v6, v3 row_half_mirror row_mask:0xf bank_mask:0xf bound_ctrl:1
	v_mov_b32_dpp v7, v5 row_half_mirror row_mask:0xf bank_mask:0xf bound_ctrl:1
	s_nop 1
	v_add_f32_dpp v204, v6, v2 quad_perm:[3,2,1,0] row_mask:0xf bank_mask:0xf bound_ctrl:1
	v_add_f32_dpp v196, v7, v4 quad_perm:[3,2,1,0] row_mask:0xf bank_mask:0xf bound_ctrl:1
	ds_read_b32 v8, v0 offset:41472
	v_mul_f32_e32 v2, 0x37638e39, v204
	v_mul_f32_e32 v3, 0x3f3504f3, v2
	v_mov_b32_e32 v4, 0xb9c68948
	v_fma_f32 v4, |v3|, s48, v4
	v_fma_f32 v4, |v3|, v4, s49
	v_fma_f32 v4, |v3|, v4, s50
	v_fma_f32 v4, |v3|, v4, s51
	v_fma_f32 v4, |v3|, v4, s52
	v_fma_f32 v4, |v3|, v4, s53
	v_fma_f32 v4, |v3|, v4, |v3|
	v_mul_f32_e32 v5, 0xbfb8aa3b, v4
	v_fma_f32 v6, v4, s54, -v5
	v_rndne_f32_e32 v7, v5
	v_fmamk_f32 v6, v4, 0xb2a5705f, v6
	v_sub_f32_e32 v5, v5, v7
	v_add_f32_e32 v5, v5, v6
	v_exp_f32_e32 v5, v5
	v_cvt_i32_f32_e32 v6, v7
	v_cmp_nlt_f32_e64 s[4:5], s55, v4
	v_ldexp_f32 v5, v5, v6
	v_mov_b32_e32 v6, 0x7f800000
	v_cndmask_b32_e64 v5, 0, v5, s[4:5]
	v_cmp_ngt_f32_e64 s[4:5], s56, v4
	v_mul_f32_e32 v7, v3, v3
	s_nop 1
	v_cndmask_b32_e64 v4, v6, v5, s[4:5]
	v_sub_f32_e32 v4, 1.0, v4
	v_mov_b32_e32 v6, 0x3ba10414
	v_fmac_f32_e32 v6, 0xba1345e1, v7
	v_fmaak_f32 v6, v7, v6, 0xbcdac9b8
	v_fmaak_f32 v6, v7, v6, 0x3de703be
	v_fmaak_f32 v6, v7, v6, 0xbec09330
	v_fmaak_f32 v7, v7, v6, 0x3e0375d0
	v_cmp_lt_f32_e64 s[4:5], |v3|, 1.0
	v_fma_f32 v7, |v3|, v7, |v3|
	v_mul_f32_e32 v2, 0.5, v2
	v_cndmask_b32_e64 v4, v4, v7, s[4:5]
	v_bfi_b32 v3, s57, v4, v3
	v_add_f32_e32 v3, 1.0, v3
	v_mul_f32_e32 v3, v2, v3
	s_waitcnt lgkmcnt(0)
; __device__ __forceinline__ float xor1(float v) { return dppf<0xB1>(v); }
; __device__ __forceinline__ float xor2(float v) { return dppf<0x4E>(v); }
; __device__ __forceinline__ float xor4s(float v) { return dppf<0x141>(v); }
; __device__ __forceinline__ float gelu_erf(float x) { return 0.5f * x * (1.f + erff(x * 0.70710678118654752f)); }
; __device__ __forceinline__ void p8_peer_gather(Frame& F) {
;     ...
;     for (int q = 0; q < 9; ++q) { const int j = q < 8 ? wave + 8 * q : 64;
; #pragma unroll
;         for (int i = 0; i < 16; ++i) { float v = (float)acc[q][i]; v += xor1(v); v += xor2(v); v += xor4s(v);
;             if (sub == 0) { if (q < 8) { const int pos = j * 128 + pg * 16 + i; cf_s[pos] = cf_pack(cf_s[pos] * gelu_erf(v * (1.f / 73728.f)) * 0.125f); } else part_s[wave * 128 + pg * 16 + i] = v; } } }
	v_mul_f32_e32 v8, v8, v3
	v_mul_f32_e32 v8, 0x3e000000, v8
	v_cvt_pk_f16_f32 v8, v8, v8
	ds_write_b32 v0, v8 offset:41472
	ds_read_b32 v8, v0 offset:41504
	v_mul_f32_e32 v2, 0x37638e39, v196
	v_mul_f32_e32 v3, 0x3f3504f3, v2
	v_mov_b32_e32 v4, 0xb9c68948
	v_fma_f32 v4, |v3|, s48, v4
	v_fma_f32 v4, |v3|, v4, s49
	v_fma_f32 v4, |v3|, v4, s50
	v_fma_f32 v4, |v3|, v4, s51
	v_fma_f32 v4, |v3|, v4, s52
	v_fma_f32 v4, |v3|, v4, s53
	v_fma_f32 v4, |v3|, v4, |v3|
	v_mul_f32_e32 v5, 0xbfb8aa3b, v4
	v_fma_f32 v6, v4, s54, -v5
	v_rndne_f32_e32 v7, v5
	v_fmamk_f32 v6, v4, 0xb2a5705f, v6
	v_sub_f32_e32 v5, v5, v7
	v_add_f32_e32 v5, v5, v6
	v_exp_f32_e32 v5, v5
	v_cvt_i32_f32_e32 v6, v7
	v_cmp_nlt_f32_e64 s[4:5], s55, v4
	v_ldexp_f32 v5, v5, v6
	v_mov_b32_e32 v6, 0x7f800000
	v_cndmask_b32_e64 v5, 0, v5, s[4:5]
	v_cmp_ngt_f32_e64 s[4:5], s56, v4
	v_mul_f32_e32 v7, v3, v3
	s_nop 1
	v_cndmask_b32_e64 v4, v6, v5, s[4:5]
	v_sub_f32_e32 v4, 1.0, v4
	v_mov_b32_e32 v6, 0x3ba10414
	v_fmac_f32_e32 v6, 0xba1345e1, v7
	v_fmaak_f32 v6, v7, v6, 0xbcdac9b8
	v_fmaak_f32 v6, v7, v6, 0x3de703be
	v_fmaak_f32 v6, v7, v6, 0xbec09330
	v_fmaak_f32 v7, v7, v6, 0x3e0375d0
	v_cmp_lt_f32_e64 s[4:5], |v3|, 1.0
	v_fma_f32 v7, |v3|, v7, |v3|
	v_mul_f32_e32 v2, 0.5, v2
	v_cndmask_b32_e64 v4, v4, v7, s[4:5]
	v_bfi_b32 v3, s57, v4, v3
	v_add_f32_e32 v3, 1.0, v3
	v_mul_f32_e32 v3, v2, v3
	s_waitcnt lgkmcnt(0)
	v_mul_f32_e32 v8, v8, v3
	v_mul_f32_e32 v8, 0x3e000000, v8
	v_cvt_pk_f16_f32 v8, v8, v8
	ds_write_b32 v0, v8 offset:41504
	v_cvt_f32_i32_e32 v188, v188
	v_cvt_f32_i32_e32 v187, v187
	v_cvt_f32_i32_e32 v186, v186
	v_cvt_f32_i32_e32 v185, v185
	v_cvt_f32_i32_e32 v184, v184
	v_cvt_f32_i32_e32 v183, v183
	v_cvt_f32_i32_e32 v182, v182
	v_cvt_f32_i32_e32 v181, v181
	v_cvt_f32_i32_e32 v180, v180
	v_cvt_f32_i32_e32 v179, v179
	v_cvt_f32_i32_e32 v178, v178
	v_cvt_f32_i32_e32 v177, v177
	v_cvt_f32_i32_e32 v176, v176
	v_cvt_f32_i32_e32 v175, v175
	v_cvt_f32_i32_e32 v174, v174
	v_cvt_f32_i32_e32 v173, v173
	v_cndmask_b32_e64 v3, v187, v188, s[42:43]
	v_cndmask_b32_e64 v5, v185, v186, s[42:43]
	v_cndmask_b32_e64 v2, v188, v187, s[42:43]
	v_cndmask_b32_e64 v4, v186, v185, s[42:43]
	v_add_f32_dpp v188, v3, v2 quad_perm:[1,0,3,2] row_mask:0xf bank_mask:0xf bound_ctrl:1
	v_add_f32_dpp v186, v5, v4 quad_perm:[1,0,3,2] row_mask:0xf bank_mask:0xf bound_ctrl:1
	v_cndmask_b32_e64 v3, v183, v184, s[42:43]
	v_cndmask_b32_e64 v5, v181, v182, s[42:43]
	v_cndmask_b32_e64 v2, v184, v183, s[42:43]
	v_cndmask_b32_e64 v4, v182, v181, s[42:43]
	v_add_f32_dpp v184, v3, v2 quad_perm:[1,0,3,2] row_mask:0xf bank_mask:0xf bound_ctrl:1
	v_add_f32_dpp v182, v5, v4 quad_perm:[1,0,3,2] row_mask:0xf bank_mask:0xf bound_ctrl:1
	v_cndmask_b32_e64 v3, v179, v180, s[42:43]
	v_cndmask_b32_e64 v5, v177, v178, s[42:43]
	v_cndmask_b32_e64 v2, v180, v179, s[42:43]
	v_cndmask_b32_e64 v4, v178, v177, s[42:43]
	v_add_f32_dpp v180, v3, v2 quad_perm:[1,0,3,2] row_mask:0xf bank_mask:0xf bound_ctrl:1
	v_add_f32_dpp v178, v5, v4 quad_perm:[1,0,3,2] row_mask:0xf bank_mask:0xf bound_ctrl:1
	v_cndmask_b32_e64 v3, v175, v176, s[42:43]
	v_cndmask_b32_e64 v5, v173, v174, s[42:43]
	v_cndmask_b32_e64 v2, v176, v175, s[42:43]
	v_cndmask_b32_e64 v4, v174, v173, s[42:43]
	v_add_f32_dpp v176, v3, v2 quad_perm:[1,0,3,2] row_mask:0xf bank_mask:0xf bound_ctrl:1
	v_add_f32_dpp v174, v5, v4 quad_perm:[1,0,3,2] row_mask:0xf bank_mask:0xf bound_ctrl:1
	v_cndmask_b32_e64 v3, v186, v188, s[44:45]
	v_cndmask_b32_e64 v5, v182, v184, s[44:45]
	v_cndmask_b32_e64 v2, v188, v186, s[44:45]
	v_cndmask_b32_e64 v4, v184, v182, s[44:45]
	v_add_f32_dpp v188, v3, v2 quad_perm:[2,3,0,1] row_mask:0xf bank_mask:0xf bound_ctrl:1
	v_add_f32_dpp v184, v5, v4 quad_perm:[2,3,0,1] row_mask:0xf bank_mask:0xf bound_ctrl:1
	v_cndmask_b32_e64 v3, v178, v180, s[44:45]
	v_cndmask_b32_e64 v5, v174, v176, s[44:45]
	v_cndmask_b32_e64 v2, v180, v178, s[44:45]
	v_cndmask_b32_e64 v4, v176, v174, s[44:45]
	v_add_f32_dpp v180, v3, v2 quad_perm:[2,3,0,1] row_mask:0xf bank_mask:0xf bound_ctrl:1
	v_add_f32_dpp v176, v5, v4 quad_perm:[2,3,0,1] row_mask:0xf bank_mask:0xf bound_ctrl:1
	v_cndmask_b32_e64 v3, v184, v188, s[46:47]
	v_cndmask_b32_e64 v5, v176, v180, s[46:47]
	v_cndmask_b32_e64 v2, v188, v184, s[46:47]
	v_cndmask_b32_e64 v4, v180, v176, s[46:47]
	v_mov_b32_dpp v6, v3 row_half_mirror row_mask:0xf bank_mask:0xf bound_ctrl:1
	v_mov_b32_dpp v7, v5 row_half_mirror row_mask:0xf bank_mask:0xf bound_ctrl:1
	s_nop 1
	v_add_f32_dpp v188, v6, v2 quad_perm:[3,2,1,0] row_mask:0xf bank_mask:0xf bound_ctrl:1
	v_add_f32_dpp v180, v7, v4 quad_perm:[3,2,1,0] row_mask:0xf bank_mask:0xf bound_ctrl:1
	ds_read_b32 v8, v0 offset:45568
	v_mul_f32_e32 v2, 0x37638e39, v188
	v_mul_f32_e32 v3, 0x3f3504f3, v2
	v_mov_b32_e32 v4, 0xb9c68948
	v_fma_f32 v4, |v3|, s48, v4
	v_fma_f32 v4, |v3|, v4, s49
	v_fma_f32 v4, |v3|, v4, s50
	v_fma_f32 v4, |v3|, v4, s51
	v_fma_f32 v4, |v3|, v4, s52
	v_fma_f32 v4, |v3|, v4, s53
	v_fma_f32 v4, |v3|, v4, |v3|
	v_mul_f32_e32 v5, 0xbfb8aa3b, v4
	v_fma_f32 v6, v4, s54, -v5
	v_rndne_f32_e32 v7, v5
	v_fmamk_f32 v6, v4, 0xb2a5705f, v6
	v_sub_f32_e32 v5, v5, v7
	v_add_f32_e32 v5, v5, v6
	v_exp_f32_e32 v5, v5
	v_cvt_i32_f32_e32 v6, v7
	v_cmp_nlt_f32_e64 s[4:5], s55, v4
	v_ldexp_f32 v5, v5, v6
	v_mov_b32_e32 v6, 0x7f800000
	v_cndmask_b32_e64 v5, 0, v5, s[4:5]
	v_cmp_ngt_f32_e64 s[4:5], s56, v4
	v_mul_f32_e32 v7, v3, v3
	s_nop 1
	v_cndmask_b32_e64 v4, v6, v5, s[4:5]
	v_sub_f32_e32 v4, 1.0, v4
	v_mov_b32_e32 v6, 0x3ba10414
	v_fmac_f32_e32 v6, 0xba1345e1, v7
	v_fmaak_f32 v6, v7, v6, 0xbcdac9b8
	v_fmaak_f32 v6, v7, v6, 0x3de703be
	v_fmaak_f32 v6, v7, v6, 0xbec09330
	v_fmaak_f32 v7, v7, v6, 0x3e0375d0
	v_cmp_lt_f32_e64 s[4:5], |v3|, 1.0
	v_fma_f32 v7, |v3|, v7, |v3|
	v_mul_f32_e32 v2, 0.5, v2
	v_cndmask_b32_e64 v4, v4, v7, s[4:5]
	v_bfi_b32 v3, s57, v4, v3
	v_add_f32_e32 v3, 1.0, v3
	v_mul_f32_e32 v3, v2, v3
	s_waitcnt lgkmcnt(0)
; __device__ __forceinline__ float xor1(float v) { return dppf<0xB1>(v); }
; __device__ __forceinline__ float xor2(float v) { return dppf<0x4E>(v); }
; __device__ __forceinline__ float xor4s(float v) { return dppf<0x141>(v); }
; __device__ __forceinline__ float gelu_erf(float x) { return 0.5f * x * (1.f + erff(x * 0.70710678118654752f)); }
; __device__ __forceinline__ void p8_peer_gather(Frame& F) {
;     ...
;     for (int q = 0; q < 9; ++q) { const int j = q < 8 ? wave + 8 * q : 64;
; #pragma unroll
;         for (int i = 0; i < 16; ++i) { float v = (float)acc[q][i]; v += xor1(v); v += xor2(v); v += xor4s(v);
;             if (sub == 0) { if (q < 8) { const int pos = j * 128 + pg * 16 + i; cf_s[pos] = cf_pack(cf_s[pos] * gelu_erf(v * (1.f / 73728.f)) * 0.125f); } else part_s[wave * 128 + pg * 16 + i] = v; } } }
	v_mul_f32_e32 v8, v8, v3
	v_mul_f32_e32 v8, 0x3e000000, v8
	v_cvt_pk_f16_f32 v8, v8, v8
	ds_write_b32 v0, v8 offset:45568
	ds_read_b32 v8, v0 offset:45600
	v_mul_f32_e32 v2, 0x37638e39, v180
	v_mul_f32_e32 v3, 0x3f3504f3, v2
	v_mov_b32_e32 v4, 0xb9c68948
	v_fma_f32 v4, |v3|, s48, v4
	v_fma_f32 v4, |v3|, v4, s49
	v_fma_f32 v4, |v3|, v4, s50
	v_fma_f32 v4, |v3|, v4, s51
	v_fma_f32 v4, |v3|, v4, s52
	v_fma_f32 v4, |v3|, v4, s53
	v_fma_f32 v4, |v3|, v4, |v3|
	v_mul_f32_e32 v5, 0xbfb8aa3b, v4
	v_fma_f32 v6, v4, s54, -v5
	v_rndne_f32_e32 v7, v5
	v_fmamk_f32 v6, v4, 0xb2a5705f, v6
	v_sub_f32_e32 v5, v5, v7
	v_add_f32_e32 v5, v5, v6
	v_exp_f32_e32 v5, v5
	v_cvt_i32_f32_e32 v6, v7
	v_cmp_nlt_f32_e64 s[4:5], s55, v4
	v_ldexp_f32 v5, v5, v6
	v_mov_b32_e32 v6, 0x7f800000
	v_cndmask_b32_e64 v5, 0, v5, s[4:5]
	v_cmp_ngt_f32_e64 s[4:5], s56, v4
	v_mul_f32_e32 v7, v3, v3
	s_nop 1
	v_cndmask_b32_e64 v4, v6, v5, s[4:5]
	v_sub_f32_e32 v4, 1.0, v4
	v_mov_b32_e32 v6, 0x3ba10414
	v_fmac_f32_e32 v6, 0xba1345e1, v7
	v_fmaak_f32 v6, v7, v6, 0xbcdac9b8
	v_fmaak_f32 v6, v7, v6, 0x3de703be
	v_fmaak_f32 v6, v7, v6, 0xbec09330
	v_fmaak_f32 v7, v7, v6, 0x3e0375d0
	v_cmp_lt_f32_e64 s[4:5], |v3|, 1.0
	v_fma_f32 v7, |v3|, v7, |v3|
	v_mul_f32_e32 v2, 0.5, v2
	v_cndmask_b32_e64 v4, v4, v7, s[4:5]
	v_bfi_b32 v3, s57, v4, v3
	v_add_f32_e32 v3, 1.0, v3
	v_mul_f32_e32 v3, v2, v3
	s_waitcnt lgkmcnt(0)
	v_mul_f32_e32 v8, v8, v3
	v_mul_f32_e32 v8, 0x3e000000, v8
	v_cvt_pk_f16_f32 v8, v8, v8
	ds_write_b32 v0, v8 offset:45600
	v_cvt_f32_i32_e32 v172, v172
	v_cvt_f32_i32_e32 v171, v171
	v_cvt_f32_i32_e32 v170, v170
	v_cvt_f32_i32_e32 v169, v169
	v_cvt_f32_i32_e32 v168, v168
	v_cvt_f32_i32_e32 v167, v167
	v_cvt_f32_i32_e32 v166, v166
	v_cvt_f32_i32_e32 v165, v165
	v_cvt_f32_i32_e32 v164, v164
	v_cvt_f32_i32_e32 v163, v163
	v_cvt_f32_i32_e32 v162, v162
	v_cvt_f32_i32_e32 v161, v161
	v_cvt_f32_i32_e32 v160, v160
	v_cvt_f32_i32_e32 v159, v159
	v_cvt_f32_i32_e32 v158, v158
	v_cvt_f32_i32_e32 v157, v157
	v_cndmask_b32_e64 v3, v171, v172, s[42:43]
	v_cndmask_b32_e64 v5, v169, v170, s[42:43]
	v_cndmask_b32_e64 v2, v172, v171, s[42:43]
	v_cndmask_b32_e64 v4, v170, v169, s[42:43]
	v_add_f32_dpp v172, v3, v2 quad_perm:[1,0,3,2] row_mask:0xf bank_mask:0xf bound_ctrl:1
	v_add_f32_dpp v170, v5, v4 quad_perm:[1,0,3,2] row_mask:0xf bank_mask:0xf bound_ctrl:1
	v_cndmask_b32_e64 v3, v167, v168, s[42:43]
	v_cndmask_b32_e64 v5, v165, v166, s[42:43]
	v_cndmask_b32_e64 v2, v168, v167, s[42:43]
	v_cndmask_b32_e64 v4, v166, v165, s[42:43]
	v_add_f32_dpp v168, v3, v2 quad_perm:[1,0,3,2] row_mask:0xf bank_mask:0xf bound_ctrl:1
	v_add_f32_dpp v166, v5, v4 quad_perm:[1,0,3,2] row_mask:0xf bank_mask:0xf bound_ctrl:1
	v_cndmask_b32_e64 v3, v163, v164, s[42:43]
	v_cndmask_b32_e64 v5, v161, v162, s[42:43]
	v_cndmask_b32_e64 v2, v164, v163, s[42:43]
	v_cndmask_b32_e64 v4, v162, v161, s[42:43]
	v_add_f32_dpp v164, v3, v2 quad_perm:[1,0,3,2] row_mask:0xf bank_mask:0xf bound_ctrl:1
	v_add_f32_dpp v162, v5, v4 quad_perm:[1,0,3,2] row_mask:0xf bank_mask:0xf bound_ctrl:1
	v_cndmask_b32_e64 v3, v159, v160, s[42:43]
	v_cndmask_b32_e64 v5, v157, v158, s[42:43]
	v_cndmask_b32_e64 v2, v160, v159, s[42:43]
	v_cndmask_b32_e64 v4, v158, v157, s[42:43]
	v_add_f32_dpp v160, v3, v2 quad_perm:[1,0,3,2] row_mask:0xf bank_mask:0xf bound_ctrl:1
	v_add_f32_dpp v158, v5, v4 quad_perm:[1,0,3,2] row_mask:0xf bank_mask:0xf bound_ctrl:1
	v_cndmask_b32_e64 v3, v170, v172, s[44:45]
	v_cndmask_b32_e64 v5, v166, v168, s[44:45]
	v_cndmask_b32_e64 v2, v172, v170, s[44:45]
	v_cndmask_b32_e64 v4, v168, v166, s[44:45]
	v_add_f32_dpp v172, v3, v2 quad_perm:[2,3,0,1] row_mask:0xf bank_mask:0xf bound_ctrl:1
	v_add_f32_dpp v168, v5, v4 quad_perm:[2,3,0,1] row_mask:0xf bank_mask:0xf bound_ctrl:1
	v_cndmask_b32_e64 v3, v162, v164, s[44:45]
	v_cndmask_b32_e64 v5, v158, v160, s[44:45]
	v_cndmask_b32_e64 v2, v164, v162, s[44:45]
	v_cndmask_b32_e64 v4, v160, v158, s[44:45]
	v_add_f32_dpp v164, v3, v2 quad_perm:[2,3,0,1] row_mask:0xf bank_mask:0xf bound_ctrl:1
	v_add_f32_dpp v160, v5, v4 quad_perm:[2,3,0,1] row_mask:0xf bank_mask:0xf bound_ctrl:1
	v_cndmask_b32_e64 v3, v168, v172, s[46:47]
	v_cndmask_b32_e64 v5, v160, v164, s[46:47]
	v_cndmask_b32_e64 v2, v172, v168, s[46:47]
	v_cndmask_b32_e64 v4, v164, v160, s[46:47]
	v_mov_b32_dpp v6, v3 row_half_mirror row_mask:0xf bank_mask:0xf bound_ctrl:1
	v_mov_b32_dpp v7, v5 row_half_mirror row_mask:0xf bank_mask:0xf bound_ctrl:1
	s_nop 1
	v_add_f32_dpp v172, v6, v2 quad_perm:[3,2,1,0] row_mask:0xf bank_mask:0xf bound_ctrl:1
	v_add_f32_dpp v164, v7, v4 quad_perm:[3,2,1,0] row_mask:0xf bank_mask:0xf bound_ctrl:1
	ds_read_b32 v8, v0 offset:49664
	v_mul_f32_e32 v2, 0x37638e39, v172
	v_mul_f32_e32 v3, 0x3f3504f3, v2
	v_mov_b32_e32 v4, 0xb9c68948
	v_fma_f32 v4, |v3|, s48, v4
	v_fma_f32 v4, |v3|, v4, s49
	v_fma_f32 v4, |v3|, v4, s50
	v_fma_f32 v4, |v3|, v4, s51
	v_fma_f32 v4, |v3|, v4, s52
	v_fma_f32 v4, |v3|, v4, s53
	v_fma_f32 v4, |v3|, v4, |v3|
	v_mul_f32_e32 v5, 0xbfb8aa3b, v4
	v_fma_f32 v6, v4, s54, -v5
	v_rndne_f32_e32 v7, v5
	v_fmamk_f32 v6, v4, 0xb2a5705f, v6
	v_sub_f32_e32 v5, v5, v7
	v_add_f32_e32 v5, v5, v6
	v_exp_f32_e32 v5, v5
	v_cvt_i32_f32_e32 v6, v7
	v_cmp_nlt_f32_e64 s[4:5], s55, v4
	v_ldexp_f32 v5, v5, v6
	v_mov_b32_e32 v6, 0x7f800000
	v_cndmask_b32_e64 v5, 0, v5, s[4:5]
	v_cmp_ngt_f32_e64 s[4:5], s56, v4
	v_mul_f32_e32 v7, v3, v3
	s_nop 1
	v_cndmask_b32_e64 v4, v6, v5, s[4:5]
	v_sub_f32_e32 v4, 1.0, v4
	v_mov_b32_e32 v6, 0x3ba10414
	v_fmac_f32_e32 v6, 0xba1345e1, v7
	v_fmaak_f32 v6, v7, v6, 0xbcdac9b8
	v_fmaak_f32 v6, v7, v6, 0x3de703be
	v_fmaak_f32 v6, v7, v6, 0xbec09330
	v_fmaak_f32 v7, v7, v6, 0x3e0375d0
	v_cmp_lt_f32_e64 s[4:5], |v3|, 1.0
	v_fma_f32 v7, |v3|, v7, |v3|
	v_mul_f32_e32 v2, 0.5, v2
	v_cndmask_b32_e64 v4, v4, v7, s[4:5]
	v_bfi_b32 v3, s57, v4, v3
	v_add_f32_e32 v3, 1.0, v3
	v_mul_f32_e32 v3, v2, v3
	s_waitcnt lgkmcnt(0)
; __device__ __forceinline__ float xor1(float v) { return dppf<0xB1>(v); }
; __device__ __forceinline__ float xor2(float v) { return dppf<0x4E>(v); }
; __device__ __forceinline__ float xor4s(float v) { return dppf<0x141>(v); }
; __device__ __forceinline__ float gelu_erf(float x) { return 0.5f * x * (1.f + erff(x * 0.70710678118654752f)); }
; __device__ __forceinline__ void p8_peer_gather(Frame& F) {
;     ...
;     for (int q = 0; q < 9; ++q) { const int j = q < 8 ? wave + 8 * q : 64;
; #pragma unroll
;         for (int i = 0; i < 16; ++i) { float v = (float)acc[q][i]; v += xor1(v); v += xor2(v); v += xor4s(v);
;             if (sub == 0) { if (q < 8) { const int pos = j * 128 + pg * 16 + i; cf_s[pos] = cf_pack(cf_s[pos] * gelu_erf(v * (1.f / 73728.f)) * 0.125f); } else part_s[wave * 128 + pg * 16 + i] = v; } } }
	v_mul_f32_e32 v8, v8, v3
	v_mul_f32_e32 v8, 0x3e000000, v8
	v_cvt_pk_f16_f32 v8, v8, v8
	ds_write_b32 v0, v8 offset:49664
	ds_read_b32 v8, v0 offset:49696
	v_mul_f32_e32 v2, 0x37638e39, v164
	v_mul_f32_e32 v3, 0x3f3504f3, v2
	v_mov_b32_e32 v4, 0xb9c68948
	v_fma_f32 v4, |v3|, s48, v4
	v_fma_f32 v4, |v3|, v4, s49
	v_fma_f32 v4, |v3|, v4, s50
	v_fma_f32 v4, |v3|, v4, s51
	v_fma_f32 v4, |v3|, v4, s52
	v_fma_f32 v4, |v3|, v4, s53
	v_fma_f32 v4, |v3|, v4, |v3|
	v_mul_f32_e32 v5, 0xbfb8aa3b, v4
	v_fma_f32 v6, v4, s54, -v5
	v_rndne_f32_e32 v7, v5
	v_fmamk_f32 v6, v4, 0xb2a5705f, v6
	v_sub_f32_e32 v5, v5, v7
	v_add_f32_e32 v5, v5, v6
	v_exp_f32_e32 v5, v5
	v_cvt_i32_f32_e32 v6, v7
	v_cmp_nlt_f32_e64 s[4:5], s55, v4
	v_ldexp_f32 v5, v5, v6
	v_mov_b32_e32 v6, 0x7f800000
	v_cndmask_b32_e64 v5, 0, v5, s[4:5]
	v_cmp_ngt_f32_e64 s[4:5], s56, v4
	v_mul_f32_e32 v7, v3, v3
	s_nop 1
	v_cndmask_b32_e64 v4, v6, v5, s[4:5]
	v_sub_f32_e32 v4, 1.0, v4
	v_mov_b32_e32 v6, 0x3ba10414
	v_fmac_f32_e32 v6, 0xba1345e1, v7
	v_fmaak_f32 v6, v7, v6, 0xbcdac9b8
	v_fmaak_f32 v6, v7, v6, 0x3de703be
	v_fmaak_f32 v6, v7, v6, 0xbec09330
	v_fmaak_f32 v7, v7, v6, 0x3e0375d0
	v_cmp_lt_f32_e64 s[4:5], |v3|, 1.0
	v_fma_f32 v7, |v3|, v7, |v3|
	v_mul_f32_e32 v2, 0.5, v2
	v_cndmask_b32_e64 v4, v4, v7, s[4:5]
	v_bfi_b32 v3, s57, v4, v3
	v_add_f32_e32 v3, 1.0, v3
	v_mul_f32_e32 v3, v2, v3
	s_waitcnt lgkmcnt(0)
	v_mul_f32_e32 v8, v8, v3
	v_mul_f32_e32 v8, 0x3e000000, v8
	v_cvt_pk_f16_f32 v8, v8, v8
	ds_write_b32 v0, v8 offset:49696
	v_cvt_f32_i32_e32 v156, v156
	v_cvt_f32_i32_e32 v155, v155
	v_cvt_f32_i32_e32 v154, v154
	v_cvt_f32_i32_e32 v153, v153
	v_cvt_f32_i32_e32 v152, v152
	v_cvt_f32_i32_e32 v151, v151
	v_cvt_f32_i32_e32 v150, v150
	v_cvt_f32_i32_e32 v149, v149
	v_cvt_f32_i32_e32 v148, v148
	v_cvt_f32_i32_e32 v147, v147
	v_cvt_f32_i32_e32 v146, v146
	v_cvt_f32_i32_e32 v145, v145
	v_cvt_f32_i32_e32 v144, v144
	v_cvt_f32_i32_e32 v143, v143
	v_cvt_f32_i32_e32 v142, v142
	v_cvt_f32_i32_e32 v141, v141
	v_cndmask_b32_e64 v3, v155, v156, s[42:43]
	v_cndmask_b32_e64 v5, v153, v154, s[42:43]
	v_cndmask_b32_e64 v2, v156, v155, s[42:43]
	v_cndmask_b32_e64 v4, v154, v153, s[42:43]
	v_add_f32_dpp v156, v3, v2 quad_perm:[1,0,3,2] row_mask:0xf bank_mask:0xf bound_ctrl:1
	v_add_f32_dpp v154, v5, v4 quad_perm:[1,0,3,2] row_mask:0xf bank_mask:0xf bound_ctrl:1
	v_cndmask_b32_e64 v3, v151, v152, s[42:43]
	v_cndmask_b32_e64 v5, v149, v150, s[42:43]
	v_cndmask_b32_e64 v2, v152, v151, s[42:43]
	v_cndmask_b32_e64 v4, v150, v149, s[42:43]
	v_add_f32_dpp v152, v3, v2 quad_perm:[1,0,3,2] row_mask:0xf bank_mask:0xf bound_ctrl:1
	v_add_f32_dpp v150, v5, v4 quad_perm:[1,0,3,2] row_mask:0xf bank_mask:0xf bound_ctrl:1
	v_cndmask_b32_e64 v3, v147, v148, s[42:43]
	v_cndmask_b32_e64 v5, v145, v146, s[42:43]
	v_cndmask_b32_e64 v2, v148, v147, s[42:43]
	v_cndmask_b32_e64 v4, v146, v145, s[42:43]
	v_add_f32_dpp v148, v3, v2 quad_perm:[1,0,3,2] row_mask:0xf bank_mask:0xf bound_ctrl:1
	v_add_f32_dpp v146, v5, v4 quad_perm:[1,0,3,2] row_mask:0xf bank_mask:0xf bound_ctrl:1
	v_cndmask_b32_e64 v3, v143, v144, s[42:43]
	v_cndmask_b32_e64 v5, v141, v142, s[42:43]
	v_cndmask_b32_e64 v2, v144, v143, s[42:43]
	v_cndmask_b32_e64 v4, v142, v141, s[42:43]
	v_add_f32_dpp v144, v3, v2 quad_perm:[1,0,3,2] row_mask:0xf bank_mask:0xf bound_ctrl:1
	v_add_f32_dpp v142, v5, v4 quad_perm:[1,0,3,2] row_mask:0xf bank_mask:0xf bound_ctrl:1
	v_cndmask_b32_e64 v3, v154, v156, s[44:45]
	v_cndmask_b32_e64 v5, v150, v152, s[44:45]
	v_cndmask_b32_e64 v2, v156, v154, s[44:45]
	v_cndmask_b32_e64 v4, v152, v150, s[44:45]
	v_add_f32_dpp v156, v3, v2 quad_perm:[2,3,0,1] row_mask:0xf bank_mask:0xf bound_ctrl:1
	v_add_f32_dpp v152, v5, v4 quad_perm:[2,3,0,1] row_mask:0xf bank_mask:0xf bound_ctrl:1
	v_cndmask_b32_e64 v3, v146, v148, s[44:45]
	v_cndmask_b32_e64 v5, v142, v144, s[44:45]
	v_cndmask_b32_e64 v2, v148, v146, s[44:45]
	v_cndmask_b32_e64 v4, v144, v142, s[44:45]
	v_add_f32_dpp v148, v3, v2 quad_perm:[2,3,0,1] row_mask:0xf bank_mask:0xf bound_ctrl:1
	v_add_f32_dpp v144, v5, v4 quad_perm:[2,3,0,1] row_mask:0xf bank_mask:0xf bound_ctrl:1
	v_cndmask_b32_e64 v3, v152, v156, s[46:47]
	v_cndmask_b32_e64 v5, v144, v148, s[46:47]
	v_cndmask_b32_e64 v2, v156, v152, s[46:47]
	v_cndmask_b32_e64 v4, v148, v144, s[46:47]
	v_mov_b32_dpp v6, v3 row_half_mirror row_mask:0xf bank_mask:0xf bound_ctrl:1
	v_mov_b32_dpp v7, v5 row_half_mirror row_mask:0xf bank_mask:0xf bound_ctrl:1
	s_nop 1
	v_add_f32_dpp v156, v6, v2 quad_perm:[3,2,1,0] row_mask:0xf bank_mask:0xf bound_ctrl:1
	v_add_f32_dpp v148, v7, v4 quad_perm:[3,2,1,0] row_mask:0xf bank_mask:0xf bound_ctrl:1
	ds_read_b32 v8, v0 offset:53760
	v_mul_f32_e32 v2, 0x37638e39, v156
	v_mul_f32_e32 v3, 0x3f3504f3, v2
	v_mov_b32_e32 v4, 0xb9c68948
	v_fma_f32 v4, |v3|, s48, v4
	v_fma_f32 v4, |v3|, v4, s49
	v_fma_f32 v4, |v3|, v4, s50
	v_fma_f32 v4, |v3|, v4, s51
	v_fma_f32 v4, |v3|, v4, s52
	v_fma_f32 v4, |v3|, v4, s53
	v_fma_f32 v4, |v3|, v4, |v3|
	v_mul_f32_e32 v5, 0xbfb8aa3b, v4
	v_fma_f32 v6, v4, s54, -v5
	v_rndne_f32_e32 v7, v5
	v_fmamk_f32 v6, v4, 0xb2a5705f, v6
	v_sub_f32_e32 v5, v5, v7
	v_add_f32_e32 v5, v5, v6
	v_exp_f32_e32 v5, v5
	v_cvt_i32_f32_e32 v6, v7
	v_cmp_nlt_f32_e64 s[4:5], s55, v4
	v_ldexp_f32 v5, v5, v6
	v_mov_b32_e32 v6, 0x7f800000
	v_cndmask_b32_e64 v5, 0, v5, s[4:5]
	v_cmp_ngt_f32_e64 s[4:5], s56, v4
	v_mul_f32_e32 v7, v3, v3
	s_nop 1
	v_cndmask_b32_e64 v4, v6, v5, s[4:5]
	v_sub_f32_e32 v4, 1.0, v4
	v_mov_b32_e32 v6, 0x3ba10414
	v_fmac_f32_e32 v6, 0xba1345e1, v7
	v_fmaak_f32 v6, v7, v6, 0xbcdac9b8
	v_fmaak_f32 v6, v7, v6, 0x3de703be
	v_fmaak_f32 v6, v7, v6, 0xbec09330
	v_fmaak_f32 v7, v7, v6, 0x3e0375d0
	v_cmp_lt_f32_e64 s[4:5], |v3|, 1.0
	v_fma_f32 v7, |v3|, v7, |v3|
	v_mul_f32_e32 v2, 0.5, v2
	v_cndmask_b32_e64 v4, v4, v7, s[4:5]
	v_bfi_b32 v3, s57, v4, v3
	v_add_f32_e32 v3, 1.0, v3
	v_mul_f32_e32 v3, v2, v3
	s_waitcnt lgkmcnt(0)
; __device__ __forceinline__ float xor1(float v) { return dppf<0xB1>(v); }
; __device__ __forceinline__ float xor2(float v) { return dppf<0x4E>(v); }
; __device__ __forceinline__ float xor4s(float v) { return dppf<0x141>(v); }
; __device__ __forceinline__ float gelu_erf(float x) { return 0.5f * x * (1.f + erff(x * 0.70710678118654752f)); }
; __device__ __forceinline__ void p8_peer_gather(Frame& F) {
;     ...
;     for (int q = 0; q < 9; ++q) { const int j = q < 8 ? wave + 8 * q : 64;
; #pragma unroll
;         for (int i = 0; i < 16; ++i) { float v = (float)acc[q][i]; v += xor1(v); v += xor2(v); v += xor4s(v);
;             if (sub == 0) { if (q < 8) { const int pos = j * 128 + pg * 16 + i; cf_s[pos] = cf_pack(cf_s[pos] * gelu_erf(v * (1.f / 73728.f)) * 0.125f); } else part_s[wave * 128 + pg * 16 + i] = v; } } }
	v_mul_f32_e32 v8, v8, v3
	v_mul_f32_e32 v8, 0x3e000000, v8
	v_cvt_pk_f16_f32 v8, v8, v8
	ds_write_b32 v0, v8 offset:53760
	ds_read_b32 v8, v0 offset:53792
	v_mul_f32_e32 v2, 0x37638e39, v148
	v_mul_f32_e32 v3, 0x3f3504f3, v2
	v_mov_b32_e32 v4, 0xb9c68948
	v_fma_f32 v4, |v3|, s48, v4
	v_fma_f32 v4, |v3|, v4, s49
	v_fma_f32 v4, |v3|, v4, s50
	v_fma_f32 v4, |v3|, v4, s51
	v_fma_f32 v4, |v3|, v4, s52
	v_fma_f32 v4, |v3|, v4, s53
	v_fma_f32 v4, |v3|, v4, |v3|
	v_mul_f32_e32 v5, 0xbfb8aa3b, v4
	v_fma_f32 v6, v4, s54, -v5
	v_rndne_f32_e32 v7, v5
	v_fmamk_f32 v6, v4, 0xb2a5705f, v6
	v_sub_f32_e32 v5, v5, v7
	v_add_f32_e32 v5, v5, v6
	v_exp_f32_e32 v5, v5
	v_cvt_i32_f32_e32 v6, v7
	v_cmp_nlt_f32_e64 s[4:5], s55, v4
	v_ldexp_f32 v5, v5, v6
	v_mov_b32_e32 v6, 0x7f800000
	v_cndmask_b32_e64 v5, 0, v5, s[4:5]
	v_cmp_ngt_f32_e64 s[4:5], s56, v4
	v_mul_f32_e32 v7, v3, v3
	s_nop 1
	v_cndmask_b32_e64 v4, v6, v5, s[4:5]
	v_sub_f32_e32 v4, 1.0, v4
	v_mov_b32_e32 v6, 0x3ba10414
	v_fmac_f32_e32 v6, 0xba1345e1, v7
	v_fmaak_f32 v6, v7, v6, 0xbcdac9b8
	v_fmaak_f32 v6, v7, v6, 0x3de703be
	v_fmaak_f32 v6, v7, v6, 0xbec09330
	v_fmaak_f32 v7, v7, v6, 0x3e0375d0
	v_cmp_lt_f32_e64 s[4:5], |v3|, 1.0
	v_fma_f32 v7, |v3|, v7, |v3|
	v_mul_f32_e32 v2, 0.5, v2
	v_cndmask_b32_e64 v4, v4, v7, s[4:5]
	v_bfi_b32 v3, s57, v4, v3
	v_add_f32_e32 v3, 1.0, v3
	v_mul_f32_e32 v3, v2, v3
	s_waitcnt lgkmcnt(0)
	v_mul_f32_e32 v8, v8, v3
	v_mul_f32_e32 v8, 0x3e000000, v8
	v_cvt_pk_f16_f32 v8, v8, v8
	ds_write_b32 v0, v8 offset:53792
	v_cvt_f32_i32_e32 v140, v140
	v_cvt_f32_i32_e32 v139, v139
	v_cvt_f32_i32_e32 v138, v138
	v_cvt_f32_i32_e32 v137, v137
	v_cvt_f32_i32_e32 v136, v136
	v_cvt_f32_i32_e32 v135, v135
	v_cvt_f32_i32_e32 v134, v134
	v_cvt_f32_i32_e32 v133, v133
	v_cvt_f32_i32_e32 v132, v132
	v_cvt_f32_i32_e32 v131, v131
	v_cvt_f32_i32_e32 v130, v130
	v_cvt_f32_i32_e32 v129, v129
	v_cvt_f32_i32_e32 v128, v128
	v_cvt_f32_i32_e32 v127, v127
	v_cvt_f32_i32_e32 v126, v126
	v_cvt_f32_i32_e32 v125, v125
	v_cndmask_b32_e64 v3, v139, v140, s[42:43]
	v_cndmask_b32_e64 v5, v137, v138, s[42:43]
	v_cndmask_b32_e64 v2, v140, v139, s[42:43]
	v_cndmask_b32_e64 v4, v138, v137, s[42:43]
	v_add_f32_dpp v140, v3, v2 quad_perm:[1,0,3,2] row_mask:0xf bank_mask:0xf bound_ctrl:1
	v_add_f32_dpp v138, v5, v4 quad_perm:[1,0,3,2] row_mask:0xf bank_mask:0xf bound_ctrl:1
	v_cndmask_b32_e64 v3, v135, v136, s[42:43]
	v_cndmask_b32_e64 v5, v133, v134, s[42:43]
	v_cndmask_b32_e64 v2, v136, v135, s[42:43]
	v_cndmask_b32_e64 v4, v134, v133, s[42:43]
	v_add_f32_dpp v136, v3, v2 quad_perm:[1,0,3,2] row_mask:0xf bank_mask:0xf bound_ctrl:1
	v_add_f32_dpp v134, v5, v4 quad_perm:[1,0,3,2] row_mask:0xf bank_mask:0xf bound_ctrl:1
	v_cndmask_b32_e64 v3, v131, v132, s[42:43]
	v_cndmask_b32_e64 v5, v129, v130, s[42:43]
	v_cndmask_b32_e64 v2, v132, v131, s[42:43]
	v_cndmask_b32_e64 v4, v130, v129, s[42:43]
	v_add_f32_dpp v132, v3, v2 quad_perm:[1,0,3,2] row_mask:0xf bank_mask:0xf bound_ctrl:1
	v_add_f32_dpp v130, v5, v4 quad_perm:[1,0,3,2] row_mask:0xf bank_mask:0xf bound_ctrl:1
	v_cndmask_b32_e64 v3, v127, v128, s[42:43]
	v_cndmask_b32_e64 v5, v125, v126, s[42:43]
	v_cndmask_b32_e64 v2, v128, v127, s[42:43]
	v_cndmask_b32_e64 v4, v126, v125, s[42:43]
	v_add_f32_dpp v128, v3, v2 quad_perm:[1,0,3,2] row_mask:0xf bank_mask:0xf bound_ctrl:1
	v_add_f32_dpp v126, v5, v4 quad_perm:[1,0,3,2] row_mask:0xf bank_mask:0xf bound_ctrl:1
	v_cndmask_b32_e64 v3, v138, v140, s[44:45]
	v_cndmask_b32_e64 v5, v134, v136, s[44:45]
	v_cndmask_b32_e64 v2, v140, v138, s[44:45]
	v_cndmask_b32_e64 v4, v136, v134, s[44:45]
	v_add_f32_dpp v140, v3, v2 quad_perm:[2,3,0,1] row_mask:0xf bank_mask:0xf bound_ctrl:1
	v_add_f32_dpp v136, v5, v4 quad_perm:[2,3,0,1] row_mask:0xf bank_mask:0xf bound_ctrl:1
	v_cndmask_b32_e64 v3, v130, v132, s[44:45]
	v_cndmask_b32_e64 v5, v126, v128, s[44:45]
	v_cndmask_b32_e64 v2, v132, v130, s[44:45]
	v_cndmask_b32_e64 v4, v128, v126, s[44:45]
	v_add_f32_dpp v132, v3, v2 quad_perm:[2,3,0,1] row_mask:0xf bank_mask:0xf bound_ctrl:1
	v_add_f32_dpp v128, v5, v4 quad_perm:[2,3,0,1] row_mask:0xf bank_mask:0xf bound_ctrl:1
	v_cndmask_b32_e64 v3, v136, v140, s[46:47]
	v_cndmask_b32_e64 v5, v128, v132, s[46:47]
	v_cndmask_b32_e64 v2, v140, v136, s[46:47]
	v_cndmask_b32_e64 v4, v132, v128, s[46:47]
	v_mov_b32_dpp v6, v3 row_half_mirror row_mask:0xf bank_mask:0xf bound_ctrl:1
	v_mov_b32_dpp v7, v5 row_half_mirror row_mask:0xf bank_mask:0xf bound_ctrl:1
	s_nop 1
	v_add_f32_dpp v140, v6, v2 quad_perm:[3,2,1,0] row_mask:0xf bank_mask:0xf bound_ctrl:1
	v_add_f32_dpp v132, v7, v4 quad_perm:[3,2,1,0] row_mask:0xf bank_mask:0xf bound_ctrl:1
	ds_read_b32 v8, v0 offset:57856
	v_mul_f32_e32 v2, 0x37638e39, v140
	v_mul_f32_e32 v3, 0x3f3504f3, v2
	v_mov_b32_e32 v4, 0xb9c68948
	v_fma_f32 v4, |v3|, s48, v4
	v_fma_f32 v4, |v3|, v4, s49
	v_fma_f32 v4, |v3|, v4, s50
	v_fma_f32 v4, |v3|, v4, s51
	v_fma_f32 v4, |v3|, v4, s52
	v_fma_f32 v4, |v3|, v4, s53
	v_fma_f32 v4, |v3|, v4, |v3|
	v_mul_f32_e32 v5, 0xbfb8aa3b, v4
	v_fma_f32 v6, v4, s54, -v5
	v_rndne_f32_e32 v7, v5
	v_fmamk_f32 v6, v4, 0xb2a5705f, v6
	v_sub_f32_e32 v5, v5, v7
	v_add_f32_e32 v5, v5, v6
	v_exp_f32_e32 v5, v5
	v_cvt_i32_f32_e32 v6, v7
	v_cmp_nlt_f32_e64 s[4:5], s55, v4
	v_ldexp_f32 v5, v5, v6
	v_mov_b32_e32 v6, 0x7f800000
	v_cndmask_b32_e64 v5, 0, v5, s[4:5]
	v_cmp_ngt_f32_e64 s[4:5], s56, v4
	v_mul_f32_e32 v7, v3, v3
	s_nop 1
	v_cndmask_b32_e64 v4, v6, v5, s[4:5]
	v_sub_f32_e32 v4, 1.0, v4
	v_mov_b32_e32 v6, 0x3ba10414
	v_fmac_f32_e32 v6, 0xba1345e1, v7
	v_fmaak_f32 v6, v7, v6, 0xbcdac9b8
	v_fmaak_f32 v6, v7, v6, 0x3de703be
	v_fmaak_f32 v6, v7, v6, 0xbec09330
	v_fmaak_f32 v7, v7, v6, 0x3e0375d0
	v_cmp_lt_f32_e64 s[4:5], |v3|, 1.0
	v_fma_f32 v7, |v3|, v7, |v3|
	v_mul_f32_e32 v2, 0.5, v2
	v_cndmask_b32_e64 v4, v4, v7, s[4:5]
	v_bfi_b32 v3, s57, v4, v3
	v_add_f32_e32 v3, 1.0, v3
	v_mul_f32_e32 v3, v2, v3
	s_waitcnt lgkmcnt(0)
; __device__ __forceinline__ float xor1(float v) { return dppf<0xB1>(v); }
; __device__ __forceinline__ float xor2(float v) { return dppf<0x4E>(v); }
; __device__ __forceinline__ float xor4s(float v) { return dppf<0x141>(v); }
; __device__ __forceinline__ float gelu_erf(float x) { return 0.5f * x * (1.f + erff(x * 0.70710678118654752f)); }
; __device__ __forceinline__ void p8_peer_gather(Frame& F) {
;     ...
;     for (int q = 0; q < 9; ++q) { const int j = q < 8 ? wave + 8 * q : 64;
; #pragma unroll
;         for (int i = 0; i < 16; ++i) { float v = (float)acc[q][i]; v += xor1(v); v += xor2(v); v += xor4s(v);
;             if (sub == 0) { if (q < 8) { const int pos = j * 128 + pg * 16 + i; cf_s[pos] = cf_pack(cf_s[pos] * gelu_erf(v * (1.f / 73728.f)) * 0.125f); } else part_s[wave * 128 + pg * 16 + i] = v; } } }
	v_mul_f32_e32 v8, v8, v3
	v_mul_f32_e32 v8, 0x3e000000, v8
	v_cvt_pk_f16_f32 v8, v8, v8
	ds_write_b32 v0, v8 offset:57856
	ds_read_b32 v8, v0 offset:57888
	v_mul_f32_e32 v2, 0x37638e39, v132
	v_mul_f32_e32 v3, 0x3f3504f3, v2
	v_mov_b32_e32 v4, 0xb9c68948
	v_fma_f32 v4, |v3|, s48, v4
	v_fma_f32 v4, |v3|, v4, s49
	v_fma_f32 v4, |v3|, v4, s50
	v_fma_f32 v4, |v3|, v4, s51
	v_fma_f32 v4, |v3|, v4, s52
	v_fma_f32 v4, |v3|, v4, s53
	v_fma_f32 v4, |v3|, v4, |v3|
	v_mul_f32_e32 v5, 0xbfb8aa3b, v4
	v_fma_f32 v6, v4, s54, -v5
	v_rndne_f32_e32 v7, v5
	v_fmamk_f32 v6, v4, 0xb2a5705f, v6
	v_sub_f32_e32 v5, v5, v7
	v_add_f32_e32 v5, v5, v6
	v_exp_f32_e32 v5, v5
	v_cvt_i32_f32_e32 v6, v7
	v_cmp_nlt_f32_e64 s[4:5], s55, v4
	v_ldexp_f32 v5, v5, v6
	v_mov_b32_e32 v6, 0x7f800000
	v_cndmask_b32_e64 v5, 0, v5, s[4:5]
	v_cmp_ngt_f32_e64 s[4:5], s56, v4
	v_mul_f32_e32 v7, v3, v3
	s_nop 1
	v_cndmask_b32_e64 v4, v6, v5, s[4:5]
	v_sub_f32_e32 v4, 1.0, v4
	v_mov_b32_e32 v6, 0x3ba10414
	v_fmac_f32_e32 v6, 0xba1345e1, v7
	v_fmaak_f32 v6, v7, v6, 0xbcdac9b8
	v_fmaak_f32 v6, v7, v6, 0x3de703be
	v_fmaak_f32 v6, v7, v6, 0xbec09330
	v_fmaak_f32 v7, v7, v6, 0x3e0375d0
	v_cmp_lt_f32_e64 s[4:5], |v3|, 1.0
	v_fma_f32 v7, |v3|, v7, |v3|
	v_mul_f32_e32 v2, 0.5, v2
	v_cndmask_b32_e64 v4, v4, v7, s[4:5]
	v_bfi_b32 v3, s57, v4, v3
	v_add_f32_e32 v3, 1.0, v3
	v_mul_f32_e32 v3, v2, v3
	s_waitcnt lgkmcnt(0)
	v_mul_f32_e32 v8, v8, v3
	v_mul_f32_e32 v8, 0x3e000000, v8
	v_cvt_pk_f16_f32 v8, v8, v8
	ds_write_b32 v0, v8 offset:57888
	v_cvt_f32_i32_e32 v124, v124
	v_cvt_f32_i32_e32 v123, v123
	v_cvt_f32_i32_e32 v122, v122
	v_cvt_f32_i32_e32 v121, v121
	v_cvt_f32_i32_e32 v120, v120
	v_cvt_f32_i32_e32 v119, v119
	v_cvt_f32_i32_e32 v118, v118
	v_cvt_f32_i32_e32 v117, v117
	v_cvt_f32_i32_e32 v116, v116
	v_cvt_f32_i32_e32 v115, v115
	v_cvt_f32_i32_e32 v114, v114
	v_cvt_f32_i32_e32 v113, v113
	v_cvt_f32_i32_e32 v112, v112
	v_cvt_f32_i32_e32 v111, v111
	v_cvt_f32_i32_e32 v110, v110
	v_cvt_f32_i32_e32 v109, v109
	v_cndmask_b32_e64 v3, v123, v124, s[42:43]
	v_cndmask_b32_e64 v5, v121, v122, s[42:43]
	v_cndmask_b32_e64 v2, v124, v123, s[42:43]
	v_cndmask_b32_e64 v4, v122, v121, s[42:43]
	v_add_f32_dpp v124, v3, v2 quad_perm:[1,0,3,2] row_mask:0xf bank_mask:0xf bound_ctrl:1
	v_add_f32_dpp v122, v5, v4 quad_perm:[1,0,3,2] row_mask:0xf bank_mask:0xf bound_ctrl:1
	v_cndmask_b32_e64 v3, v119, v120, s[42:43]
	v_cndmask_b32_e64 v5, v117, v118, s[42:43]
	v_cndmask_b32_e64 v2, v120, v119, s[42:43]
	v_cndmask_b32_e64 v4, v118, v117, s[42:43]
	v_add_f32_dpp v120, v3, v2 quad_perm:[1,0,3,2] row_mask:0xf bank_mask:0xf bound_ctrl:1
	v_add_f32_dpp v118, v5, v4 quad_perm:[1,0,3,2] row_mask:0xf bank_mask:0xf bound_ctrl:1
	v_cndmask_b32_e64 v3, v115, v116, s[42:43]
	v_cndmask_b32_e64 v5, v113, v114, s[42:43]
	v_cndmask_b32_e64 v2, v116, v115, s[42:43]
	v_cndmask_b32_e64 v4, v114, v113, s[42:43]
	v_add_f32_dpp v116, v3, v2 quad_perm:[1,0,3,2] row_mask:0xf bank_mask:0xf bound_ctrl:1
	v_add_f32_dpp v114, v5, v4 quad_perm:[1,0,3,2] row_mask:0xf bank_mask:0xf bound_ctrl:1
	v_cndmask_b32_e64 v3, v111, v112, s[42:43]
	v_cndmask_b32_e64 v5, v109, v110, s[42:43]
	v_cndmask_b32_e64 v2, v112, v111, s[42:43]
	v_cndmask_b32_e64 v4, v110, v109, s[42:43]
	v_add_f32_dpp v112, v3, v2 quad_perm:[1,0,3,2] row_mask:0xf bank_mask:0xf bound_ctrl:1
	v_add_f32_dpp v110, v5, v4 quad_perm:[1,0,3,2] row_mask:0xf bank_mask:0xf bound_ctrl:1
	v_cndmask_b32_e64 v3, v122, v124, s[44:45]
	v_cndmask_b32_e64 v5, v118, v120, s[44:45]
	v_cndmask_b32_e64 v2, v124, v122, s[44:45]
	v_cndmask_b32_e64 v4, v120, v118, s[44:45]
	v_add_f32_dpp v124, v3, v2 quad_perm:[2,3,0,1] row_mask:0xf bank_mask:0xf bound_ctrl:1
	v_add_f32_dpp v120, v5, v4 quad_perm:[2,3,0,1] row_mask:0xf bank_mask:0xf bound_ctrl:1
	v_cndmask_b32_e64 v3, v114, v116, s[44:45]
	v_cndmask_b32_e64 v5, v110, v112, s[44:45]
	v_cndmask_b32_e64 v2, v116, v114, s[44:45]
	v_cndmask_b32_e64 v4, v112, v110, s[44:45]
	v_add_f32_dpp v116, v3, v2 quad_perm:[2,3,0,1] row_mask:0xf bank_mask:0xf bound_ctrl:1
	v_add_f32_dpp v112, v5, v4 quad_perm:[2,3,0,1] row_mask:0xf bank_mask:0xf bound_ctrl:1
	v_cndmask_b32_e64 v3, v120, v124, s[46:47]
	v_cndmask_b32_e64 v5, v112, v116, s[46:47]
	v_cndmask_b32_e64 v2, v124, v120, s[46:47]
	v_cndmask_b32_e64 v4, v116, v112, s[46:47]
	v_mov_b32_dpp v6, v3 row_half_mirror row_mask:0xf bank_mask:0xf bound_ctrl:1
	v_mov_b32_dpp v7, v5 row_half_mirror row_mask:0xf bank_mask:0xf bound_ctrl:1
	s_nop 1
	v_add_f32_dpp v124, v6, v2 quad_perm:[3,2,1,0] row_mask:0xf bank_mask:0xf bound_ctrl:1
	v_add_f32_dpp v116, v7, v4 quad_perm:[3,2,1,0] row_mask:0xf bank_mask:0xf bound_ctrl:1
	ds_read_b32 v8, v0 offset:61952
	v_mul_f32_e32 v2, 0x37638e39, v124
	v_mul_f32_e32 v3, 0x3f3504f3, v2
	v_mov_b32_e32 v4, 0xb9c68948
	v_fma_f32 v4, |v3|, s48, v4
	v_fma_f32 v4, |v3|, v4, s49
	v_fma_f32 v4, |v3|, v4, s50
	v_fma_f32 v4, |v3|, v4, s51
	v_fma_f32 v4, |v3|, v4, s52
	v_fma_f32 v4, |v3|, v4, s53
	v_fma_f32 v4, |v3|, v4, |v3|
	v_mul_f32_e32 v5, 0xbfb8aa3b, v4
	v_fma_f32 v6, v4, s54, -v5
	v_rndne_f32_e32 v7, v5
	v_fmamk_f32 v6, v4, 0xb2a5705f, v6
	v_sub_f32_e32 v5, v5, v7
	v_add_f32_e32 v5, v5, v6
	v_exp_f32_e32 v5, v5
	v_cvt_i32_f32_e32 v6, v7
	v_cmp_nlt_f32_e64 s[4:5], s55, v4
	v_ldexp_f32 v5, v5, v6
	v_mov_b32_e32 v6, 0x7f800000
	v_cndmask_b32_e64 v5, 0, v5, s[4:5]
	v_cmp_ngt_f32_e64 s[4:5], s56, v4
	v_mul_f32_e32 v7, v3, v3
	s_nop 1
	v_cndmask_b32_e64 v4, v6, v5, s[4:5]
	v_sub_f32_e32 v4, 1.0, v4
	v_mov_b32_e32 v6, 0x3ba10414
	v_fmac_f32_e32 v6, 0xba1345e1, v7
	v_fmaak_f32 v6, v7, v6, 0xbcdac9b8
	v_fmaak_f32 v6, v7, v6, 0x3de703be
	v_fmaak_f32 v6, v7, v6, 0xbec09330
	v_fmaak_f32 v7, v7, v6, 0x3e0375d0
	v_cmp_lt_f32_e64 s[4:5], |v3|, 1.0
	v_fma_f32 v7, |v3|, v7, |v3|
	v_mul_f32_e32 v2, 0.5, v2
	v_cndmask_b32_e64 v4, v4, v7, s[4:5]
	v_bfi_b32 v3, s57, v4, v3
	v_add_f32_e32 v3, 1.0, v3
	v_mul_f32_e32 v3, v2, v3
	s_waitcnt lgkmcnt(0)
; __device__ __forceinline__ float xor1(float v) { return dppf<0xB1>(v); }
; __device__ __forceinline__ float xor2(float v) { return dppf<0x4E>(v); }
; __device__ __forceinline__ float xor4s(float v) { return dppf<0x141>(v); }
; __device__ __forceinline__ float gelu_erf(float x) { return 0.5f * x * (1.f + erff(x * 0.70710678118654752f)); }
; __device__ __forceinline__ void p8_peer_gather(Frame& F) {
;     ...
;     for (int q = 0; q < 9; ++q) { const int j = q < 8 ? wave + 8 * q : 64;
; #pragma unroll
;         for (int i = 0; i < 16; ++i) { float v = (float)acc[q][i]; v += xor1(v); v += xor2(v); v += xor4s(v);
;             if (sub == 0) { if (q < 8) { const int pos = j * 128 + pg * 16 + i; cf_s[pos] = cf_pack(cf_s[pos] * gelu_erf(v * (1.f / 73728.f)) * 0.125f); } else part_s[wave * 128 + pg * 16 + i] = v; } } }
;     __syncthreads();
;     if (tid < 128) { float v = 0.f;
; #pragma unroll
;         for (int w = 0; w < 8; ++w) v += part_s[w * 128 + tid];
;         cf_s[64 * 128 + tid] = cf_pack(cf_s[64 * 128 + tid] * gelu_erf(v * (1.f / 73728.f)) * 0.125f); }
	v_mul_f32_e32 v8, v8, v3
	v_mul_f32_e32 v8, 0x3e000000, v8
	v_cvt_pk_f16_f32 v8, v8, v8
	ds_write_b32 v0, v8 offset:61952
	ds_read_b32 v8, v0 offset:61984
	v_mul_f32_e32 v2, 0x37638e39, v116
	v_mul_f32_e32 v3, 0x3f3504f3, v2
	v_mov_b32_e32 v4, 0xb9c68948
	v_fma_f32 v4, |v3|, s48, v4
	v_fma_f32 v4, |v3|, v4, s49
	v_fma_f32 v4, |v3|, v4, s50
	v_fma_f32 v4, |v3|, v4, s51
	v_fma_f32 v4, |v3|, v4, s52
	v_fma_f32 v4, |v3|, v4, s53
	v_fma_f32 v4, |v3|, v4, |v3|
	v_mul_f32_e32 v5, 0xbfb8aa3b, v4
	v_fma_f32 v6, v4, s54, -v5
	v_rndne_f32_e32 v7, v5
	v_fmamk_f32 v6, v4, 0xb2a5705f, v6
	v_sub_f32_e32 v5, v5, v7
	v_add_f32_e32 v5, v5, v6
	v_exp_f32_e32 v5, v5
	v_cvt_i32_f32_e32 v6, v7
	v_cmp_nlt_f32_e64 s[4:5], s55, v4
	v_ldexp_f32 v5, v5, v6
	v_mov_b32_e32 v6, 0x7f800000
	v_cndmask_b32_e64 v5, 0, v5, s[4:5]
	v_cmp_ngt_f32_e64 s[4:5], s56, v4
	v_mul_f32_e32 v7, v3, v3
	s_nop 1
	v_cndmask_b32_e64 v4, v6, v5, s[4:5]
	v_sub_f32_e32 v4, 1.0, v4
	v_mov_b32_e32 v6, 0x3ba10414
	v_fmac_f32_e32 v6, 0xba1345e1, v7
	v_fmaak_f32 v6, v7, v6, 0xbcdac9b8
	v_fmaak_f32 v6, v7, v6, 0x3de703be
	v_fmaak_f32 v6, v7, v6, 0xbec09330
	v_fmaak_f32 v7, v7, v6, 0x3e0375d0
	v_cmp_lt_f32_e64 s[4:5], |v3|, 1.0
	v_fma_f32 v7, |v3|, v7, |v3|
	v_mul_f32_e32 v2, 0.5, v2
	v_cndmask_b32_e64 v4, v4, v7, s[4:5]
	v_bfi_b32 v3, s57, v4, v3
	v_add_f32_e32 v3, 1.0, v3
	v_mul_f32_e32 v3, v2, v3
	s_waitcnt lgkmcnt(0)
	v_mul_f32_e32 v8, v8, v3
	v_mul_f32_e32 v8, 0x3e000000, v8
	v_cvt_pk_f16_f32 v8, v8, v8
	ds_write_b32 v0, v8 offset:61984
	v_cvt_f32_i32_e32 v108, v108
	v_cvt_f32_i32_e32 v107, v107
	v_cvt_f32_i32_e32 v106, v106
	v_cvt_f32_i32_e32 v105, v105
	v_cvt_f32_i32_e32 v104, v104
	v_cvt_f32_i32_e32 v103, v103
	v_cvt_f32_i32_e32 v102, v102
	v_cvt_f32_i32_e32 v101, v101
	v_cvt_f32_i32_e32 v100, v100
	v_cvt_f32_i32_e32 v99, v99
	v_cvt_f32_i32_e32 v98, v98
	v_cvt_f32_i32_e32 v97, v97
	v_cvt_f32_i32_e32 v96, v96
	v_cvt_f32_i32_e32 v95, v95
	v_cvt_f32_i32_e32 v91, v91
	v_cvt_f32_i32_e32 v81, v81
	v_cndmask_b32_e64 v3, v107, v108, s[42:43]
	v_cndmask_b32_e64 v5, v105, v106, s[42:43]
	v_cndmask_b32_e64 v2, v108, v107, s[42:43]
	v_cndmask_b32_e64 v4, v106, v105, s[42:43]
	v_add_f32_dpp v108, v3, v2 quad_perm:[1,0,3,2] row_mask:0xf bank_mask:0xf bound_ctrl:1
	v_add_f32_dpp v106, v5, v4 quad_perm:[1,0,3,2] row_mask:0xf bank_mask:0xf bound_ctrl:1
	v_cndmask_b32_e64 v3, v103, v104, s[42:43]
	v_cndmask_b32_e64 v5, v101, v102, s[42:43]
	v_cndmask_b32_e64 v2, v104, v103, s[42:43]
	v_cndmask_b32_e64 v4, v102, v101, s[42:43]
	v_add_f32_dpp v104, v3, v2 quad_perm:[1,0,3,2] row_mask:0xf bank_mask:0xf bound_ctrl:1
	v_add_f32_dpp v102, v5, v4 quad_perm:[1,0,3,2] row_mask:0xf bank_mask:0xf bound_ctrl:1
	v_cndmask_b32_e64 v3, v99, v100, s[42:43]
	v_cndmask_b32_e64 v5, v97, v98, s[42:43]
	v_cndmask_b32_e64 v2, v100, v99, s[42:43]
	v_cndmask_b32_e64 v4, v98, v97, s[42:43]
	v_add_f32_dpp v100, v3, v2 quad_perm:[1,0,3,2] row_mask:0xf bank_mask:0xf bound_ctrl:1
	v_add_f32_dpp v98, v5, v4 quad_perm:[1,0,3,2] row_mask:0xf bank_mask:0xf bound_ctrl:1
	v_cndmask_b32_e64 v3, v95, v96, s[42:43]
	v_cndmask_b32_e64 v5, v81, v91, s[42:43]
	v_cndmask_b32_e64 v2, v96, v95, s[42:43]
	v_cndmask_b32_e64 v4, v91, v81, s[42:43]
	v_add_f32_dpp v96, v3, v2 quad_perm:[1,0,3,2] row_mask:0xf bank_mask:0xf bound_ctrl:1
	v_add_f32_dpp v91, v5, v4 quad_perm:[1,0,3,2] row_mask:0xf bank_mask:0xf bound_ctrl:1
	v_cndmask_b32_e64 v3, v106, v108, s[44:45]
	v_cndmask_b32_e64 v5, v102, v104, s[44:45]
	v_cndmask_b32_e64 v2, v108, v106, s[44:45]
	v_cndmask_b32_e64 v4, v104, v102, s[44:45]
	v_add_f32_dpp v108, v3, v2 quad_perm:[2,3,0,1] row_mask:0xf bank_mask:0xf bound_ctrl:1
	v_add_f32_dpp v104, v5, v4 quad_perm:[2,3,0,1] row_mask:0xf bank_mask:0xf bound_ctrl:1
	v_cndmask_b32_e64 v3, v98, v100, s[44:45]
	v_cndmask_b32_e64 v5, v91, v96, s[44:45]
	v_cndmask_b32_e64 v2, v100, v98, s[44:45]
	v_cndmask_b32_e64 v4, v96, v91, s[44:45]
	v_add_f32_dpp v100, v3, v2 quad_perm:[2,3,0,1] row_mask:0xf bank_mask:0xf bound_ctrl:1
	v_add_f32_dpp v96, v5, v4 quad_perm:[2,3,0,1] row_mask:0xf bank_mask:0xf bound_ctrl:1
	v_cndmask_b32_e64 v3, v104, v108, s[46:47]
	v_cndmask_b32_e64 v5, v96, v100, s[46:47]
	v_cndmask_b32_e64 v2, v108, v104, s[46:47]
	v_cndmask_b32_e64 v4, v100, v96, s[46:47]
	v_mov_b32_dpp v6, v3 row_half_mirror row_mask:0xf bank_mask:0xf bound_ctrl:1
	v_mov_b32_dpp v7, v5 row_half_mirror row_mask:0xf bank_mask:0xf bound_ctrl:1
	s_nop 1
	v_add_f32_dpp v108, v6, v2 quad_perm:[3,2,1,0] row_mask:0xf bank_mask:0xf bound_ctrl:1
	v_add_f32_dpp v100, v7, v4 quad_perm:[3,2,1,0] row_mask:0xf bank_mask:0xf bound_ctrl:1
	ds_write_b32 v1, v108 offset:0
	ds_write_b32 v1, v100 offset:32
	s_waitcnt lgkmcnt(0)
	s_barrier
	s_and_saveexec_b64 s[4:5], s[0:1]
	s_cbranch_execz .LBB0_2581
	v_lshl_add_u32 v0, v89, 2, 0
	v_add_u32_e32 v1, 0x10400, v0
	ds_read2st64_b32 v[2:3], v1 offset1:2
	ds_read2st64_b32 v[4:5], v1 offset0:4 offset1:6
	ds_read2st64_b32 v[6:7], v1 offset0:8 offset1:10
	ds_read2st64_b32 v[8:9], v1 offset0:12 offset1:14
	v_add_u32_e32 v0, 0x8200, v0
	s_waitcnt lgkmcnt(3)
	v_add_f32_e32 v1, 0, v2
	v_add_f32_e32 v1, v1, v3
	s_waitcnt lgkmcnt(2)
	v_add_f32_e32 v1, v1, v4
	v_add_f32_e32 v1, v1, v5
	s_waitcnt lgkmcnt(1)
	v_add_f32_e32 v1, v1, v6
	v_add_f32_e32 v1, v1, v7
	s_waitcnt lgkmcnt(0)
	v_add_f32_e32 v2, v1, v8
	ds_read_b32 v1, v0 offset:32768
	v_add_f32_e32 v2, v2, v9
	v_mul_f32_e32 v3, 0x37638e39, v2
	v_mul_f32_e32 v2, 0x3f3504f3, v3
	v_cmp_nlt_f32_e64 s[0:1], |v2|, 1.0
	s_and_saveexec_b64 s[2:3], s[0:1]
	s_xor_b64 s[0:1], exec, s[2:3]
	s_cbranch_execz .LBB0_2578
	s_mov_b32 s2, 0x378e98ab
	v_mov_b32_e32 v4, 0xb9c68948
	v_fma_f32 v4, |v2|, s2, v4
	s_mov_b32 s2, 0x3b7cd369
	v_fma_f32 v4, |v2|, v4, s2
	s_mov_b32 s2, 0xbcc618b2
	v_fma_f32 v4, |v2|, v4, s2
	s_mov_b32 s2, 0x3dda74e4
	v_fma_f32 v4, |v2|, v4, s2
	s_mov_b32 s2, 0x3f228afd
	v_fma_f32 v4, |v2|, v4, s2
	s_mov_b32 s2, 0x3e03c728
	v_fma_f32 v4, |v2|, v4, s2
	v_fma_f32 v4, |v2|, v4, |v2|
	s_mov_b32 s2, 0xbfb8aa3b
	v_mul_f32_e32 v5, 0xbfb8aa3b, v4
	v_fma_f32 v6, v4, s2, -v5
	v_rndne_f32_e32 v7, v5
	v_fmamk_f32 v6, v4, 0xb2a5705f, v6
	v_sub_f32_e32 v5, v5, v7
	v_add_f32_e32 v5, v5, v6
	v_exp_f32_e32 v5, v5
	v_cvt_i32_f32_e32 v6, v7
	s_mov_b32 s2, 0x42ce8ed0
	v_cmp_nlt_f32_e32 vcc, s2, v4
	s_mov_b32 s2, 0xc2b17218
	v_ldexp_f32 v5, v5, v6
	v_cndmask_b32_e32 v5, 0, v5, vcc
	v_mov_b32_e32 v6, 0x7f800000
	v_cmp_ngt_f32_e32 vcc, s2, v4
	s_nop 1
	v_cndmask_b32_e32 v4, v6, v5, vcc
	v_sub_f32_e32 v4, 1.0, v4
